# epilogue cross-lane sums: ds_bpermute (+address calc) replaced by v_permlane16/32_swap in P1 norm, P6 and P8 rssp reductions
# baseline (speedup 1.0000x reference)
.LBB0_510:
	s_and_b64 s[70:71], s[8:9], s[4:5]
	s_ashr_i32 s4, s76, 11
	s_mul_i32 s4, s65, s4
	s_add_i32 s4, s4, s63
	s_ashr_i32 s5, s4, 31
	v_lshl_add_u64 v[180:181], v[178:179], 0, v[152:153]
	s_lshl_b64 s[4:5], s[4:5], 18
	v_cndmask_b32_e64 v0, 0, 1, s[74:75]
	v_lshl_add_u64 v[182:183], v[180:181], 0, s[4:5]
	s_andn2_b64 vcc, exec, s[10:11]
	v_cmp_ne_u32_e64 s[10:11], 1, v0
	s_cbranch_vccnz .LBB0_517
	s_and_b64 vcc, exec, s[10:11]
	s_cbranch_vccnz .LBB0_632
	v_mul_f32_e32 v4, v17, v17
	v_fmac_f32_e32 v4, v16, v16
	v_fmac_f32_e32 v4, v18, v18
	v_fmac_f32_e32 v4, v19, v19
	v_fmac_f32_e32 v4, v20, v20
	v_fmac_f32_e32 v4, v21, v21
	v_fmac_f32_e32 v4, v22, v22
	v_fmac_f32_e32 v4, v23, v23
	v_pk_mul_f32 v[2:3], v[24:25], v[24:25]
	v_pk_mul_f32 v[0:1], v[26:27], v[26:27]
	v_add_f32_e32 v2, v2, v4
	v_add_f32_e32 v2, v3, v2
	v_add_f32_e32 v0, v0, v2
	v_add_f32_e32 v4, v1, v0
	v_pk_mul_f32 v[2:3], v[28:29], v[28:29]
	v_pk_mul_f32 v[0:1], v[30:31], v[30:31]
	v_add_f32_e32 v2, v2, v4
	v_add_f32_e32 v2, v3, v2
	v_add_f32_e32 v0, v0, v2
	v_add_f32_e32 v0, v1, v0
	v_mov_b32_e32 v1, v0
	s_nop 1
	v_permlane16_swap_b32_e32 v0, v1
	s_waitcnt lgkmcnt(0)
	v_add_f32_e32 v0, v0, v1
	v_mov_b32_e32 v1, v0
	s_nop 1
	v_permlane32_swap_b32_e32 v0, v1
	s_waitcnt lgkmcnt(0)
	v_add_f32_e32 v0, v0, v1
	s_waitcnt vmcnt(0)
	v_mul_f32_e32 v1, v150, v150
	v_mul_f32_e32 v0, v1, v0
	v_fmamk_f32 v0, v0, 0x3c800000, v194
	v_mul_f32_e32 v1, 0x4b800000, v0
	v_cmp_gt_f32_e32 vcc, s42, v0
	s_nop 1
	v_cndmask_b32_e32 v0, v0, v1, vcc
	v_rsq_f32_e32 v0, v0
	s_nop 0
	v_mul_f32_e32 v1, 0x45800000, v0
	v_cndmask_b32_e32 v0, v0, v1, vcc
	v_mul_f32_e32 v0, v150, v0
	v_pk_mul_f32 v[186:187], v[16:17], v[0:1] op_sel_hi:[1,0]
	v_pk_mul_f32 v[2:3], v[18:19], v[0:1] op_sel_hi:[1,0]
	v_pk_mul_f32 v[4:5], v[20:21], v[0:1] op_sel_hi:[1,0]
	v_pk_mul_f32 v[6:7], v[22:23], v[0:1] op_sel_hi:[1,0]
	v_pk_mul_f32 v[8:9], v[24:25], v[0:1] op_sel_hi:[1,0]
	v_pk_mul_f32 v[10:11], v[26:27], v[0:1] op_sel_hi:[1,0]
	v_pk_mul_f32 v[12:13], v[28:29], v[0:1] op_sel_hi:[1,0]
	v_pk_mul_f32 v[0:1], v[30:31], v[0:1] op_sel_hi:[1,0]
	v_pk_mul_f32 v[12:13], v[174:175], v[12:13]
	v_pk_mul_f32 v[14:15], v[176:177], v[0:1]
	v_pk_mul_f32 v[10:11], v[172:173], v[10:11]
	v_pk_mul_f32 v[8:9], v[170:171], v[8:9]
	v_pk_mul_f32 v[6:7], v[168:169], v[6:7]
	v_pk_mul_f32 v[4:5], v[166:167], v[4:5]
	v_pk_mul_f32 v[2:3], v[164:165], v[2:3]
	v_pk_mul_f32 v[0:1], v[162:163], v[186:187]
	s_cbranch_execnz .LBB0_514

.LBB0_526:
	s_andn2_b64 vcc, exec, s[4:5]
	s_cbranch_vccnz .LBB0_533
	s_and_b64 vcc, exec, s[10:11]
	s_cbranch_vccnz .LBB0_633
	v_mul_f32_e32 v4, v129, v129
	v_fmac_f32_e32 v4, v128, v128
	v_fmac_f32_e32 v4, v130, v130
	v_fmac_f32_e32 v4, v131, v131
	v_fmac_f32_e32 v4, v132, v132
	v_fmac_f32_e32 v4, v133, v133
	v_fmac_f32_e32 v4, v134, v134
	v_fmac_f32_e32 v4, v135, v135
	v_pk_mul_f32 v[2:3], v[136:137], v[136:137]
	v_pk_mul_f32 v[0:1], v[138:139], v[138:139]
	v_add_f32_e32 v2, v2, v4
	v_add_f32_e32 v2, v3, v2
	v_add_f32_e32 v0, v0, v2
	v_add_f32_e32 v4, v1, v0
	v_pk_mul_f32 v[2:3], v[140:141], v[140:141]
	v_pk_mul_f32 v[0:1], v[142:143], v[142:143]
	v_add_f32_e32 v2, v2, v4
	v_add_f32_e32 v2, v3, v2
	v_add_f32_e32 v0, v0, v2
	v_add_f32_e32 v0, v1, v0
	v_mov_b32_e32 v1, v0
	s_nop 1
	v_permlane16_swap_b32_e32 v0, v1
	s_waitcnt lgkmcnt(0)
	v_add_f32_e32 v0, v0, v1
	v_mov_b32_e32 v1, v0
	s_nop 1
	v_permlane32_swap_b32_e32 v0, v1
	s_waitcnt lgkmcnt(0)
	v_add_f32_e32 v0, v0, v1
	s_waitcnt vmcnt(0)
	v_mul_f32_e32 v1, v16, v16
	v_mul_f32_e32 v0, v1, v0
	v_fmamk_f32 v0, v0, 0x3c800000, v194
	v_mul_f32_e32 v1, 0x4b800000, v0
	v_cmp_gt_f32_e32 vcc, s42, v0
	s_nop 1
	v_cndmask_b32_e32 v0, v0, v1, vcc
	v_rsq_f32_e32 v0, v0
	s_nop 0
	v_mul_f32_e32 v1, 0x45800000, v0
	v_cndmask_b32_e32 v0, v0, v1, vcc
	v_mul_f32_e32 v0, v16, v0
	v_pk_mul_f32 v[18:19], v[128:129], v[0:1] op_sel_hi:[1,0]
	v_pk_mul_f32 v[2:3], v[130:131], v[0:1] op_sel_hi:[1,0]
	v_pk_mul_f32 v[4:5], v[132:133], v[0:1] op_sel_hi:[1,0]
	v_pk_mul_f32 v[6:7], v[134:135], v[0:1] op_sel_hi:[1,0]
	v_pk_mul_f32 v[8:9], v[136:137], v[0:1] op_sel_hi:[1,0]
	v_pk_mul_f32 v[10:11], v[138:139], v[0:1] op_sel_hi:[1,0]
	v_pk_mul_f32 v[12:13], v[140:141], v[0:1] op_sel_hi:[1,0]
	v_pk_mul_f32 v[0:1], v[142:143], v[0:1] op_sel_hi:[1,0]
	v_pk_mul_f32 v[12:13], v[174:175], v[12:13]
	v_pk_mul_f32 v[14:15], v[176:177], v[0:1]
	v_pk_mul_f32 v[10:11], v[172:173], v[10:11]
	v_pk_mul_f32 v[8:9], v[170:171], v[8:9]
	v_pk_mul_f32 v[6:7], v[168:169], v[6:7]
	v_pk_mul_f32 v[4:5], v[166:167], v[4:5]
	v_pk_mul_f32 v[2:3], v[164:165], v[2:3]
	v_pk_mul_f32 v[0:1], v[162:163], v[18:19]
	s_cbranch_execnz .LBB0_530

.LBB0_542:
	s_andn2_b64 vcc, exec, s[4:5]
	s_cbranch_vccnz .LBB0_549
	s_and_b64 vcc, exec, s[10:11]
	s_cbranch_vccnz .LBB0_634
	v_mul_f32_e32 v4, v113, v113
	v_fmac_f32_e32 v4, v112, v112
	v_fmac_f32_e32 v4, v114, v114
	v_fmac_f32_e32 v4, v115, v115
	v_fmac_f32_e32 v4, v116, v116
	v_fmac_f32_e32 v4, v117, v117
	v_fmac_f32_e32 v4, v118, v118
	v_fmac_f32_e32 v4, v119, v119
	v_pk_mul_f32 v[2:3], v[120:121], v[120:121]
	v_pk_mul_f32 v[0:1], v[122:123], v[122:123]
	v_add_f32_e32 v2, v2, v4
	v_add_f32_e32 v2, v3, v2
	v_add_f32_e32 v0, v0, v2
	v_add_f32_e32 v4, v1, v0
	v_pk_mul_f32 v[2:3], v[124:125], v[124:125]
	v_pk_mul_f32 v[0:1], v[126:127], v[126:127]
	v_add_f32_e32 v2, v2, v4
	v_add_f32_e32 v2, v3, v2
	v_add_f32_e32 v0, v0, v2
	v_add_f32_e32 v0, v1, v0
	v_mov_b32_e32 v1, v0
	s_nop 1
	v_permlane16_swap_b32_e32 v0, v1
	s_waitcnt lgkmcnt(0)
	v_add_f32_e32 v0, v0, v1
	v_mov_b32_e32 v1, v0
	s_nop 1
	v_permlane32_swap_b32_e32 v0, v1
	s_waitcnt lgkmcnt(0)
	v_add_f32_e32 v0, v0, v1
	s_waitcnt vmcnt(0)
	v_mul_f32_e32 v1, v16, v16
	v_mul_f32_e32 v0, v1, v0
	v_fmamk_f32 v0, v0, 0x3c800000, v194
	v_mul_f32_e32 v1, 0x4b800000, v0
	v_cmp_gt_f32_e32 vcc, s42, v0
	s_nop 1
	v_cndmask_b32_e32 v0, v0, v1, vcc
	v_rsq_f32_e32 v0, v0
	s_nop 0
	v_mul_f32_e32 v1, 0x45800000, v0
	v_cndmask_b32_e32 v0, v0, v1, vcc
	v_mul_f32_e32 v0, v16, v0
	v_pk_mul_f32 v[18:19], v[112:113], v[0:1] op_sel_hi:[1,0]
	v_pk_mul_f32 v[2:3], v[114:115], v[0:1] op_sel_hi:[1,0]
	v_pk_mul_f32 v[4:5], v[116:117], v[0:1] op_sel_hi:[1,0]
	v_pk_mul_f32 v[6:7], v[118:119], v[0:1] op_sel_hi:[1,0]
	v_pk_mul_f32 v[8:9], v[120:121], v[0:1] op_sel_hi:[1,0]
	v_pk_mul_f32 v[10:11], v[122:123], v[0:1] op_sel_hi:[1,0]
	v_pk_mul_f32 v[12:13], v[124:125], v[0:1] op_sel_hi:[1,0]
	v_pk_mul_f32 v[0:1], v[126:127], v[0:1] op_sel_hi:[1,0]
	v_pk_mul_f32 v[12:13], v[174:175], v[12:13]
	v_pk_mul_f32 v[14:15], v[176:177], v[0:1]
	v_pk_mul_f32 v[10:11], v[172:173], v[10:11]
	v_pk_mul_f32 v[8:9], v[170:171], v[8:9]
	v_pk_mul_f32 v[6:7], v[168:169], v[6:7]
	v_pk_mul_f32 v[4:5], v[166:167], v[4:5]
	v_pk_mul_f32 v[2:3], v[164:165], v[2:3]
	v_pk_mul_f32 v[0:1], v[162:163], v[18:19]
	s_cbranch_execnz .LBB0_546

.LBB0_558:
	s_andn2_b64 vcc, exec, s[4:5]
	s_cbranch_vccnz .LBB0_565
	s_and_b64 vcc, exec, s[10:11]
	s_cbranch_vccnz .LBB0_635
	v_mul_f32_e32 v4, v97, v97
	v_fmac_f32_e32 v4, v96, v96
	v_fmac_f32_e32 v4, v98, v98
	v_fmac_f32_e32 v4, v99, v99
	v_fmac_f32_e32 v4, v100, v100
	v_fmac_f32_e32 v4, v101, v101
	v_fmac_f32_e32 v4, v102, v102
	v_fmac_f32_e32 v4, v103, v103
	v_pk_mul_f32 v[2:3], v[104:105], v[104:105]
	v_pk_mul_f32 v[0:1], v[106:107], v[106:107]
	v_add_f32_e32 v2, v2, v4
	v_add_f32_e32 v2, v3, v2
	v_add_f32_e32 v0, v0, v2
	v_add_f32_e32 v4, v1, v0
	v_pk_mul_f32 v[2:3], v[108:109], v[108:109]
	v_pk_mul_f32 v[0:1], v[110:111], v[110:111]
	v_add_f32_e32 v2, v2, v4
	v_add_f32_e32 v2, v3, v2
	v_add_f32_e32 v0, v0, v2
	v_add_f32_e32 v0, v1, v0
	v_mov_b32_e32 v1, v0
	s_nop 1
	v_permlane16_swap_b32_e32 v0, v1
	s_waitcnt lgkmcnt(0)
	v_add_f32_e32 v0, v0, v1
	v_mov_b32_e32 v1, v0
	s_nop 1
	v_permlane32_swap_b32_e32 v0, v1
	s_waitcnt lgkmcnt(0)
	v_add_f32_e32 v0, v0, v1
	s_waitcnt vmcnt(0)
	v_mul_f32_e32 v1, v16, v16
	v_mul_f32_e32 v0, v1, v0
	v_fmamk_f32 v0, v0, 0x3c800000, v194
	v_mul_f32_e32 v1, 0x4b800000, v0
	v_cmp_gt_f32_e32 vcc, s42, v0
	s_nop 1
	v_cndmask_b32_e32 v0, v0, v1, vcc
	v_rsq_f32_e32 v0, v0
	s_nop 0
	v_mul_f32_e32 v1, 0x45800000, v0
	v_cndmask_b32_e32 v0, v0, v1, vcc
	v_mul_f32_e32 v0, v16, v0
	v_pk_mul_f32 v[18:19], v[96:97], v[0:1] op_sel_hi:[1,0]
	v_pk_mul_f32 v[2:3], v[98:99], v[0:1] op_sel_hi:[1,0]
	v_pk_mul_f32 v[4:5], v[100:101], v[0:1] op_sel_hi:[1,0]
	v_pk_mul_f32 v[6:7], v[102:103], v[0:1] op_sel_hi:[1,0]
	v_pk_mul_f32 v[8:9], v[104:105], v[0:1] op_sel_hi:[1,0]
	v_pk_mul_f32 v[10:11], v[106:107], v[0:1] op_sel_hi:[1,0]
	v_pk_mul_f32 v[12:13], v[108:109], v[0:1] op_sel_hi:[1,0]
	v_pk_mul_f32 v[0:1], v[110:111], v[0:1] op_sel_hi:[1,0]
	v_pk_mul_f32 v[12:13], v[174:175], v[12:13]
	v_pk_mul_f32 v[14:15], v[176:177], v[0:1]
	v_pk_mul_f32 v[10:11], v[172:173], v[10:11]
	v_pk_mul_f32 v[8:9], v[170:171], v[8:9]
	v_pk_mul_f32 v[6:7], v[168:169], v[6:7]
	v_pk_mul_f32 v[4:5], v[166:167], v[4:5]
	v_pk_mul_f32 v[2:3], v[164:165], v[2:3]
	v_pk_mul_f32 v[0:1], v[162:163], v[18:19]
	s_cbranch_execnz .LBB0_562

.LBB0_574:
	s_ashr_i32 s72, s76, 11
	s_mul_i32 s65, s65, s72
	s_add_i32 s72, s65, s63
	s_ashr_i32 s73, s72, 31
	s_lshl_b64 s[72:73], s[72:73], 18
	s_andn2_b64 vcc, exec, s[4:5]
	v_lshl_add_u64 v[96:97], v[180:181], 0, s[72:73]
	s_cbranch_vccnz .LBB0_581
	s_and_b64 vcc, exec, s[10:11]
	s_cbranch_vccnz .LBB0_636
	v_mul_f32_e32 v4, v81, v81
	v_fmac_f32_e32 v4, v80, v80
	v_fmac_f32_e32 v4, v82, v82
	v_fmac_f32_e32 v4, v83, v83
	v_fmac_f32_e32 v4, v84, v84
	v_fmac_f32_e32 v4, v85, v85
	v_fmac_f32_e32 v4, v86, v86
	v_fmac_f32_e32 v4, v87, v87
	v_pk_mul_f32 v[2:3], v[88:89], v[88:89]
	v_pk_mul_f32 v[0:1], v[90:91], v[90:91]
	v_add_f32_e32 v2, v2, v4
	v_add_f32_e32 v2, v3, v2
	v_add_f32_e32 v0, v0, v2
	v_add_f32_e32 v4, v1, v0
	v_pk_mul_f32 v[2:3], v[92:93], v[92:93]
	v_pk_mul_f32 v[0:1], v[94:95], v[94:95]
	v_add_f32_e32 v2, v2, v4
	v_add_f32_e32 v2, v3, v2
	v_add_f32_e32 v0, v0, v2
	v_add_f32_e32 v0, v1, v0
	v_mov_b32_e32 v1, v0
	s_nop 1
	v_permlane16_swap_b32_e32 v0, v1
	s_waitcnt lgkmcnt(0)
	v_add_f32_e32 v0, v0, v1
	v_mov_b32_e32 v1, v0
	s_nop 1
	v_permlane32_swap_b32_e32 v0, v1
	s_waitcnt lgkmcnt(0)
	v_add_f32_e32 v0, v0, v1
	s_waitcnt vmcnt(0)
	v_mul_f32_e32 v1, v16, v16
	v_mul_f32_e32 v0, v1, v0
	v_fmamk_f32 v0, v0, 0x3c800000, v194
	v_mul_f32_e32 v1, 0x4b800000, v0
	v_cmp_gt_f32_e32 vcc, s42, v0
	s_nop 1
	v_cndmask_b32_e32 v0, v0, v1, vcc
	v_rsq_f32_e32 v0, v0
	s_nop 0
	v_mul_f32_e32 v1, 0x45800000, v0
	v_cndmask_b32_e32 v0, v0, v1, vcc
	v_mul_f32_e32 v0, v16, v0
	v_pk_mul_f32 v[18:19], v[80:81], v[0:1] op_sel_hi:[1,0]
	v_pk_mul_f32 v[2:3], v[82:83], v[0:1] op_sel_hi:[1,0]
	v_pk_mul_f32 v[4:5], v[84:85], v[0:1] op_sel_hi:[1,0]
	v_pk_mul_f32 v[6:7], v[86:87], v[0:1] op_sel_hi:[1,0]
	v_pk_mul_f32 v[8:9], v[88:89], v[0:1] op_sel_hi:[1,0]
	v_pk_mul_f32 v[10:11], v[90:91], v[0:1] op_sel_hi:[1,0]
	v_pk_mul_f32 v[12:13], v[92:93], v[0:1] op_sel_hi:[1,0]
	v_pk_mul_f32 v[0:1], v[94:95], v[0:1] op_sel_hi:[1,0]
	v_pk_mul_f32 v[12:13], v[174:175], v[12:13]
	v_pk_mul_f32 v[14:15], v[176:177], v[0:1]
	v_pk_mul_f32 v[10:11], v[172:173], v[10:11]
	v_pk_mul_f32 v[8:9], v[170:171], v[8:9]
	v_pk_mul_f32 v[6:7], v[168:169], v[6:7]
	v_pk_mul_f32 v[4:5], v[166:167], v[4:5]
	v_pk_mul_f32 v[2:3], v[164:165], v[2:3]
	v_pk_mul_f32 v[0:1], v[162:163], v[18:19]
	s_cbranch_execnz .LBB0_578

.LBB0_590:
	s_andn2_b64 vcc, exec, s[4:5]
	s_cbranch_vccnz .LBB0_597
	s_and_b64 vcc, exec, s[10:11]
	s_cbranch_vccnz .LBB0_637
	v_mul_f32_e32 v4, v65, v65
	v_fmac_f32_e32 v4, v64, v64
	v_fmac_f32_e32 v4, v66, v66
	v_fmac_f32_e32 v4, v67, v67
	v_fmac_f32_e32 v4, v68, v68
	v_fmac_f32_e32 v4, v69, v69
	v_fmac_f32_e32 v4, v70, v70
	v_fmac_f32_e32 v4, v71, v71
	v_pk_mul_f32 v[2:3], v[72:73], v[72:73]
	v_pk_mul_f32 v[0:1], v[74:75], v[74:75]
	v_add_f32_e32 v2, v2, v4
	v_add_f32_e32 v2, v3, v2
	v_add_f32_e32 v0, v0, v2
	v_add_f32_e32 v4, v1, v0
	v_pk_mul_f32 v[2:3], v[76:77], v[76:77]
	v_pk_mul_f32 v[0:1], v[78:79], v[78:79]
	v_add_f32_e32 v2, v2, v4
	v_add_f32_e32 v2, v3, v2
	v_add_f32_e32 v0, v0, v2
	v_add_f32_e32 v0, v1, v0
	v_mov_b32_e32 v1, v0
	s_nop 1
	v_permlane16_swap_b32_e32 v0, v1
	s_waitcnt lgkmcnt(0)
	v_add_f32_e32 v0, v0, v1
	v_mov_b32_e32 v1, v0
	s_nop 1
	v_permlane32_swap_b32_e32 v0, v1
	s_waitcnt lgkmcnt(0)
	v_add_f32_e32 v0, v0, v1
	s_waitcnt vmcnt(0)
	v_mul_f32_e32 v1, v16, v16
	v_mul_f32_e32 v0, v1, v0
	v_fmamk_f32 v0, v0, 0x3c800000, v194
	v_mul_f32_e32 v1, 0x4b800000, v0
	v_cmp_gt_f32_e32 vcc, s42, v0
	s_nop 1
	v_cndmask_b32_e32 v0, v0, v1, vcc
	v_rsq_f32_e32 v0, v0
	s_nop 0
	v_mul_f32_e32 v1, 0x45800000, v0
	v_cndmask_b32_e32 v0, v0, v1, vcc
	v_mul_f32_e32 v0, v16, v0
	v_pk_mul_f32 v[18:19], v[64:65], v[0:1] op_sel_hi:[1,0]
	v_pk_mul_f32 v[2:3], v[66:67], v[0:1] op_sel_hi:[1,0]
	v_pk_mul_f32 v[4:5], v[68:69], v[0:1] op_sel_hi:[1,0]
	v_pk_mul_f32 v[6:7], v[70:71], v[0:1] op_sel_hi:[1,0]
	v_pk_mul_f32 v[8:9], v[72:73], v[0:1] op_sel_hi:[1,0]
	v_pk_mul_f32 v[10:11], v[74:75], v[0:1] op_sel_hi:[1,0]
	v_pk_mul_f32 v[12:13], v[76:77], v[0:1] op_sel_hi:[1,0]
	v_pk_mul_f32 v[0:1], v[78:79], v[0:1] op_sel_hi:[1,0]
	v_pk_mul_f32 v[12:13], v[174:175], v[12:13]
	v_pk_mul_f32 v[14:15], v[176:177], v[0:1]
	v_pk_mul_f32 v[10:11], v[172:173], v[10:11]
	v_pk_mul_f32 v[8:9], v[170:171], v[8:9]
	v_pk_mul_f32 v[6:7], v[168:169], v[6:7]
	v_pk_mul_f32 v[4:5], v[166:167], v[4:5]
	v_pk_mul_f32 v[2:3], v[164:165], v[2:3]
	v_pk_mul_f32 v[0:1], v[162:163], v[18:19]
	s_cbranch_execnz .LBB0_594

.LBB0_606:
	s_andn2_b64 vcc, exec, s[4:5]
	s_cbranch_vccnz .LBB0_613
	s_and_b64 vcc, exec, s[10:11]
	s_cbranch_vccnz .LBB0_638
	v_mul_f32_e32 v4, v49, v49
	v_fmac_f32_e32 v4, v48, v48
	v_fmac_f32_e32 v4, v50, v50
	v_fmac_f32_e32 v4, v51, v51
	v_fmac_f32_e32 v4, v52, v52
	v_fmac_f32_e32 v4, v53, v53
	v_fmac_f32_e32 v4, v54, v54
	v_fmac_f32_e32 v4, v55, v55
	v_pk_mul_f32 v[2:3], v[56:57], v[56:57]
	v_pk_mul_f32 v[0:1], v[58:59], v[58:59]
	v_add_f32_e32 v2, v2, v4
	v_add_f32_e32 v2, v3, v2
	v_add_f32_e32 v0, v0, v2
	v_add_f32_e32 v4, v1, v0
	v_pk_mul_f32 v[2:3], v[60:61], v[60:61]
	v_pk_mul_f32 v[0:1], v[62:63], v[62:63]
	v_add_f32_e32 v2, v2, v4
	v_add_f32_e32 v2, v3, v2
	v_add_f32_e32 v0, v0, v2
	v_add_f32_e32 v0, v1, v0
	v_mov_b32_e32 v1, v0
	s_nop 1
	v_permlane16_swap_b32_e32 v0, v1
	s_waitcnt lgkmcnt(0)
	v_add_f32_e32 v0, v0, v1
	v_mov_b32_e32 v1, v0
	s_nop 1
	v_permlane32_swap_b32_e32 v0, v1
	s_waitcnt lgkmcnt(0)
	v_add_f32_e32 v0, v0, v1
	s_waitcnt vmcnt(0)
	v_mul_f32_e32 v1, v16, v16
	v_mul_f32_e32 v0, v1, v0
	v_fmamk_f32 v0, v0, 0x3c800000, v194
	v_mul_f32_e32 v1, 0x4b800000, v0
	v_cmp_gt_f32_e32 vcc, s42, v0
	s_nop 1
	v_cndmask_b32_e32 v0, v0, v1, vcc
	v_rsq_f32_e32 v0, v0
	s_nop 0
	v_mul_f32_e32 v1, 0x45800000, v0
	v_cndmask_b32_e32 v0, v0, v1, vcc
	v_mul_f32_e32 v0, v16, v0
	v_pk_mul_f32 v[18:19], v[48:49], v[0:1] op_sel_hi:[1,0]
	v_pk_mul_f32 v[2:3], v[50:51], v[0:1] op_sel_hi:[1,0]
	v_pk_mul_f32 v[4:5], v[52:53], v[0:1] op_sel_hi:[1,0]
	v_pk_mul_f32 v[6:7], v[54:55], v[0:1] op_sel_hi:[1,0]
	v_pk_mul_f32 v[8:9], v[56:57], v[0:1] op_sel_hi:[1,0]
	v_pk_mul_f32 v[10:11], v[58:59], v[0:1] op_sel_hi:[1,0]
	v_pk_mul_f32 v[12:13], v[60:61], v[0:1] op_sel_hi:[1,0]
	v_pk_mul_f32 v[0:1], v[62:63], v[0:1] op_sel_hi:[1,0]
	v_pk_mul_f32 v[12:13], v[174:175], v[12:13]
	v_pk_mul_f32 v[14:15], v[176:177], v[0:1]
	v_pk_mul_f32 v[10:11], v[172:173], v[10:11]
	v_pk_mul_f32 v[8:9], v[170:171], v[8:9]
	v_pk_mul_f32 v[6:7], v[168:169], v[6:7]
	v_pk_mul_f32 v[4:5], v[166:167], v[4:5]
	v_pk_mul_f32 v[2:3], v[164:165], v[2:3]
	v_pk_mul_f32 v[0:1], v[162:163], v[18:19]
	s_cbranch_execnz .LBB0_610

.LBB0_622:
	s_andn2_b64 vcc, exec, s[4:5]
	s_cbranch_vccnz .LBB0_629
	s_and_b64 vcc, exec, s[10:11]
	s_cbranch_vccnz .LBB0_639
	v_mul_f32_e32 v4, v37, v37
	v_fmac_f32_e32 v4, v36, v36
	v_fmac_f32_e32 v4, v38, v38
	v_fmac_f32_e32 v4, v39, v39
	v_fmac_f32_e32 v4, v40, v40
	v_fmac_f32_e32 v4, v41, v41
	v_fmac_f32_e32 v4, v42, v42
	v_fmac_f32_e32 v4, v43, v43
	v_pk_mul_f32 v[2:3], v[44:45], v[44:45]
	v_pk_mul_f32 v[0:1], v[46:47], v[46:47]
	v_add_f32_e32 v2, v2, v4
	v_add_f32_e32 v2, v3, v2
	v_add_f32_e32 v0, v0, v2
	v_add_f32_e32 v4, v1, v0
	v_pk_mul_f32 v[2:3], v[32:33], v[32:33]
	v_pk_mul_f32 v[0:1], v[34:35], v[34:35]
	v_add_f32_e32 v2, v2, v4
	v_add_f32_e32 v2, v3, v2
	v_add_f32_e32 v0, v0, v2
	v_add_f32_e32 v0, v1, v0
	v_mov_b32_e32 v1, v0
	s_nop 1
	v_permlane16_swap_b32_e32 v0, v1
	s_waitcnt lgkmcnt(0)
	v_add_f32_e32 v0, v0, v1
	v_mov_b32_e32 v1, v0
	s_nop 1
	v_permlane32_swap_b32_e32 v0, v1
	s_waitcnt lgkmcnt(0)
	v_add_f32_e32 v0, v0, v1
	s_waitcnt vmcnt(0)
	v_mul_f32_e32 v1, v16, v16
	v_mul_f32_e32 v0, v1, v0
	v_fmamk_f32 v0, v0, 0x3c800000, v194
	v_mul_f32_e32 v1, 0x4b800000, v0
	v_cmp_gt_f32_e32 vcc, s42, v0
	s_nop 1
	v_cndmask_b32_e32 v0, v0, v1, vcc
	v_rsq_f32_e32 v0, v0
	s_nop 0
	v_mul_f32_e32 v1, 0x45800000, v0
	v_cndmask_b32_e32 v0, v0, v1, vcc
	v_mul_f32_e32 v0, v16, v0
	v_pk_mul_f32 v[18:19], v[36:37], v[0:1] op_sel_hi:[1,0]
	v_pk_mul_f32 v[2:3], v[38:39], v[0:1] op_sel_hi:[1,0]
	v_pk_mul_f32 v[4:5], v[40:41], v[0:1] op_sel_hi:[1,0]
	v_pk_mul_f32 v[6:7], v[42:43], v[0:1] op_sel_hi:[1,0]
	v_pk_mul_f32 v[8:9], v[44:45], v[0:1] op_sel_hi:[1,0]
	v_pk_mul_f32 v[10:11], v[46:47], v[0:1] op_sel_hi:[1,0]
	v_pk_mul_f32 v[12:13], v[32:33], v[0:1] op_sel_hi:[1,0]
	v_pk_mul_f32 v[0:1], v[34:35], v[0:1] op_sel_hi:[1,0]
	v_pk_mul_f32 v[12:13], v[174:175], v[12:13]
	v_pk_mul_f32 v[14:15], v[176:177], v[0:1]
	v_pk_mul_f32 v[10:11], v[172:173], v[10:11]
	v_pk_mul_f32 v[8:9], v[170:171], v[8:9]
	v_pk_mul_f32 v[6:7], v[168:169], v[6:7]
	v_pk_mul_f32 v[4:5], v[166:167], v[4:5]
	v_pk_mul_f32 v[2:3], v[164:165], v[2:3]
	v_pk_mul_f32 v[0:1], v[162:163], v[18:19]
	s_cbranch_execnz .LBB0_626

.LBB0_1373:
	v_and_b32_e32 v236, 48, v144
	v_mul_u32_u24_e32 v232, 3, v236
	v_sub_u32_e32 v232, 0, v232
	v_ashrrev_i32_e32 v233, 31, v232
	v_sub_u32_e32 v236, 0, v236
	v_ashrrev_i32_e32 v237, 31, v236
	v_lshl_add_u32 v140, s30, 8, v142
	v_ashrrev_i32_e32 v141, 31, v140
	v_readlane_b32 s60, v240, 5
	v_lshl_or_b32 v138, s8, 8, v144
	v_lshlrev_b64 v[150:151], 12, v[140:141]
	v_readlane_b32 s61, v240, 6
	v_ashrrev_i32_e32 v139, 31, v138
	v_xor_b32_e32 v149, 16, v148
	v_lshl_add_u64 v[150:151], s[60:61], 0, v[150:151]
	v_lshl_add_u64 v[150:151], v[138:139], 2, v[150:151]
	v_lshl_add_u64 v[234:235], v[150:151], 0, v[232:233]
	global_load_dwordx4 v[152:155], v[234:235], off
	global_load_dwordx4 v[156:159], v[234:235], off offset:64
	global_load_dwordx4 v[160:163], v[234:235], off offset:128
	global_load_dwordx4 v[164:167], v[234:235], off offset:192
	v_and_b32_e32 v150, 64, v148
	v_add_u32_e32 v150, 64, v150
	v_cmp_lt_i32_e32 vcc, v149, v150
	v_xor_b32_e32 v151, 32, v148
	v_lshlrev_b64 v[168:169], 11, v[140:141]
	v_cndmask_b32_e32 v149, v148, v149, vcc
	v_cmp_lt_i32_e32 vcc, v151, v150
	v_lshlrev_b32_e32 v150, 2, v149
	s_lshl_b32 s30, s8, 2
	v_cndmask_b32_e32 v151, v148, v151, vcc
	v_lshlrev_b32_e32 v149, 2, v151
	v_lshl_add_u64 v[168:169], s[12:13], 0, v[168:169]
	s_ashr_i32 s31, s30, 31
	v_lshl_add_u64 v[168:169], v[138:139], 1, v[168:169]
	v_readlane_b32 s62, v240, 7
	v_readlane_b32 s63, v240, 8
	s_waitcnt vmcnt(0)
	v_permlane16_swap_b32_e32 v152, v156
	v_permlane16_swap_b32_e32 v153, v157
	v_permlane16_swap_b32_e32 v154, v158
	v_permlane16_swap_b32_e32 v155, v159
	v_permlane16_swap_b32_e32 v160, v164
	v_permlane16_swap_b32_e32 v161, v165
	v_permlane16_swap_b32_e32 v162, v166
	v_permlane16_swap_b32_e32 v163, v167
	v_permlane32_swap_b32_e32 v152, v160
	v_permlane32_swap_b32_e32 v153, v161
	v_permlane32_swap_b32_e32 v154, v162
	v_permlane32_swap_b32_e32 v155, v163
	v_permlane32_swap_b32_e32 v156, v164
	v_permlane32_swap_b32_e32 v157, v165
	v_permlane32_swap_b32_e32 v158, v166
	v_permlane32_swap_b32_e32 v159, v167
	v_pk_add_f32 v[120:121], v[120:121], v[152:153]
	v_pk_add_f32 v[122:123], v[122:123], v[154:155]
	v_pk_add_f32 v[152:153], v[118:119], v[162:163]
	v_pk_add_f32 v[118:119], v[116:117], v[160:161]
	v_pk_mul_f32 v[116:117], v[120:121], v[120:121]
	v_pk_add_f32 v[124:125], v[124:125], v[156:157]
	v_pk_add_f32 v[154:155], v[114:115], v[166:167]
	v_pk_add_f32 v[156:157], v[112:113], v[164:165]
	v_pk_mul_f32 v[112:113], v[122:123], v[122:123]
	v_add_f32_e32 v115, v116, v117
	v_add_f32_e32 v112, v112, v115
	v_pk_mul_f32 v[160:161], v[124:125], v[124:125]
	v_add_f32_e32 v112, v113, v112
	v_pk_add_f32 v[126:127], v[126:127], v[158:159]
	v_add_f32_e32 v112, v160, v112
	v_pk_mul_f32 v[158:159], v[126:127], v[126:127]
	v_add_f32_e32 v112, v161, v112
	v_add_f32_e32 v112, v158, v112
	v_pk_mul_f32 v[164:165], v[118:119], v[118:119]
	v_add_f32_e32 v112, v159, v112
	v_add_f32_e32 v112, v164, v112
	v_pk_mul_f32 v[162:163], v[152:153], v[152:153]
	v_add_f32_e32 v112, v165, v112
	v_add_f32_e32 v112, v162, v112
	v_pk_mul_f32 v[170:171], v[156:157], v[156:157]
	v_add_f32_e32 v112, v163, v112
	v_add_f32_e32 v112, v170, v112
	v_pk_mul_f32 v[166:167], v[154:155], v[154:155]
	v_add_f32_e32 v112, v171, v112
	v_add_f32_e32 v112, v166, v112
	v_add_f32_e32 v112, v167, v112
	v_mov_b32_e32 v113, v112
	s_nop 1
	v_permlane16_swap_b32_e32 v112, v113
	v_cvt_pk_bf16_f32 v114, v120, v121
	v_cvt_pk_bf16_f32 v115, v122, v123
	v_cvt_pk_bf16_f32 v116, v124, v125
	v_cvt_pk_bf16_f32 v117, v126, v127
	s_waitcnt lgkmcnt(0)
	v_add_f32_e32 v112, v112, v113
	v_mov_b32_e32 v113, v112
	s_nop 1
	v_permlane32_swap_b32_e32 v112, v113
	v_cvt_pk_bf16_f32 v118, v118, v119
	v_cvt_pk_bf16_f32 v119, v152, v153
	v_cvt_pk_bf16_f32 v120, v156, v157
	v_cvt_pk_bf16_f32 v121, v154, v155
	s_nop 1
	v_permlane16_swap_b32_e32 v114, v118
	v_permlane16_swap_b32_e32 v115, v119
	v_permlane16_swap_b32_e32 v116, v120
	v_permlane16_swap_b32_e32 v117, v121
	v_permlane32_swap_b32_e32 v114, v118
	v_permlane32_swap_b32_e32 v115, v119
	v_permlane32_swap_b32_e32 v116, v120
	v_permlane32_swap_b32_e32 v117, v121
	v_lshl_add_u64 v[238:239], v[168:169], 0, v[236:237]
	global_store_dwordx4 v[238:239], v[114:117], off
	global_store_dwordx4 v[238:239], v[118:121], off offset:64
	s_and_saveexec_b64 s[4:5], s[6:7]
	s_cbranch_execz .LBB0_1375
	v_lshlrev_b64 v[114:115], 6, v[140:141]
	v_lshl_add_u64 v[114:115], s[14:15], 0, v[114:115]
	v_lshl_add_u64 v[114:115], s[30:31], 2, v[114:115]
	s_lshl_b32 s8, s46, 2
	v_lshl_add_u64 v[114:115], v[114:115], 0, s[8:9]
	s_waitcnt lgkmcnt(0)
	v_add_f32_e32 v112, v112, v113
	global_store_dword v[114:115], v112, off
.LBB0_1375:
	s_or_b64 exec, exec, s[4:5]
	v_or_b32_e32 v112, 16, v140
	s_waitcnt lgkmcnt(0)
	v_ashrrev_i32_e32 v113, 31, v112
	v_readlane_b32 s60, v240, 5
	v_lshlrev_b64 v[114:115], 12, v[112:113]
	v_readlane_b32 s61, v240, 6
	v_readlane_b32 s62, v240, 7
	v_readlane_b32 s63, v240, 8
	v_lshl_add_u64 v[114:115], s[60:61], 0, v[114:115]
	v_lshl_add_u64 v[126:127], v[138:139], 2, v[114:115]
	v_lshl_add_u64 v[234:235], v[126:127], 0, v[232:233]
	global_load_dwordx4 v[114:117], v[234:235], off
	global_load_dwordx4 v[118:121], v[234:235], off offset:64
	global_load_dwordx4 v[122:125], v[234:235], off offset:128
	global_load_dwordx4 v[152:155], v[234:235], off offset:192
	v_lshlrev_b64 v[126:127], 11, v[112:113]
	v_lshl_add_u64 v[126:127], s[12:13], 0, v[126:127]
	v_lshl_add_u64 v[126:127], v[138:139], 1, v[126:127]
	s_waitcnt vmcnt(0)
	v_permlane16_swap_b32_e32 v114, v118
	v_permlane16_swap_b32_e32 v115, v119
	v_permlane16_swap_b32_e32 v116, v120
	v_permlane16_swap_b32_e32 v117, v121
	v_permlane16_swap_b32_e32 v122, v152
	v_permlane16_swap_b32_e32 v123, v153
	v_permlane16_swap_b32_e32 v124, v154
	v_permlane16_swap_b32_e32 v125, v155
	v_permlane32_swap_b32_e32 v114, v122
	v_permlane32_swap_b32_e32 v115, v123
	v_permlane32_swap_b32_e32 v116, v124
	v_permlane32_swap_b32_e32 v117, v125
	v_permlane32_swap_b32_e32 v118, v152
	v_permlane32_swap_b32_e32 v119, v153
	v_permlane32_swap_b32_e32 v120, v154
	v_permlane32_swap_b32_e32 v121, v155
	v_pk_add_f32 v[108:109], v[108:109], v[114:115]
	v_pk_add_f32 v[110:111], v[110:111], v[116:117]
	s_waitcnt vmcnt(1)
	v_pk_add_f32 v[114:115], v[102:103], v[124:125]
	v_pk_add_f32 v[102:103], v[100:101], v[122:123]
	v_pk_mul_f32 v[100:101], v[108:109], v[108:109]
	v_pk_add_f32 v[104:105], v[104:105], v[118:119]
	s_waitcnt vmcnt(0)
	v_pk_add_f32 v[116:117], v[98:99], v[154:155]
	v_pk_add_f32 v[118:119], v[96:97], v[152:153]
	v_pk_mul_f32 v[96:97], v[110:111], v[110:111]
	v_add_f32_e32 v99, v100, v101
	v_add_f32_e32 v96, v96, v99
	v_pk_mul_f32 v[122:123], v[104:105], v[104:105]
	v_add_f32_e32 v96, v97, v96
	v_pk_add_f32 v[106:107], v[106:107], v[120:121]
	v_add_f32_e32 v96, v122, v96
	v_pk_mul_f32 v[120:121], v[106:107], v[106:107]
	v_add_f32_e32 v96, v123, v96
	v_add_f32_e32 v96, v120, v96
	v_pk_mul_f32 v[152:153], v[102:103], v[102:103]
	v_add_f32_e32 v96, v121, v96
	v_add_f32_e32 v96, v152, v96
	v_pk_mul_f32 v[124:125], v[114:115], v[114:115]
	v_add_f32_e32 v96, v153, v96
	v_add_f32_e32 v96, v124, v96
	v_pk_mul_f32 v[156:157], v[118:119], v[118:119]
	v_add_f32_e32 v96, v125, v96
	v_add_f32_e32 v96, v156, v96
	v_pk_mul_f32 v[154:155], v[116:117], v[116:117]
	v_add_f32_e32 v96, v157, v96
	v_add_f32_e32 v96, v154, v96
	v_add_f32_e32 v96, v155, v96
	v_mov_b32_e32 v97, v96
	s_nop 1
	v_permlane16_swap_b32_e32 v96, v97
	v_cvt_pk_bf16_f32 v98, v108, v109
	v_cvt_pk_bf16_f32 v99, v110, v111
	v_cvt_pk_bf16_f32 v100, v104, v105
	v_cvt_pk_bf16_f32 v101, v106, v107
	s_waitcnt lgkmcnt(0)
	v_add_f32_e32 v96, v96, v97
	v_mov_b32_e32 v97, v96
	s_nop 1
	v_permlane32_swap_b32_e32 v96, v97
	v_cvt_pk_bf16_f32 v102, v102, v103
	v_cvt_pk_bf16_f32 v103, v114, v115
	v_cvt_pk_bf16_f32 v104, v118, v119
	v_cvt_pk_bf16_f32 v105, v116, v117
	s_nop 1
	v_permlane16_swap_b32_e32 v98, v102
	v_permlane16_swap_b32_e32 v99, v103
	v_permlane16_swap_b32_e32 v100, v104
	v_permlane16_swap_b32_e32 v101, v105
	v_permlane32_swap_b32_e32 v98, v102
	v_permlane32_swap_b32_e32 v99, v103
	v_permlane32_swap_b32_e32 v100, v104
	v_permlane32_swap_b32_e32 v101, v105
	v_lshl_add_u64 v[238:239], v[126:127], 0, v[236:237]
	global_store_dwordx4 v[238:239], v[98:101], off
	global_store_dwordx4 v[238:239], v[102:105], off offset:64
	s_and_saveexec_b64 s[4:5], s[6:7]
	s_cbranch_execz .LBB0_1377
	v_lshlrev_b64 v[98:99], 6, v[112:113]
	v_lshl_add_u64 v[98:99], s[14:15], 0, v[98:99]
	v_lshl_add_u64 v[98:99], s[30:31], 2, v[98:99]
	s_lshl_b32 s8, s46, 2
	v_lshl_add_u64 v[98:99], v[98:99], 0, s[8:9]
	s_waitcnt lgkmcnt(0)
	v_add_f32_e32 v96, v96, v97
	global_store_dword v[98:99], v96, off
.LBB0_1377:
	s_or_b64 exec, exec, s[4:5]
	v_or_b32_e32 v96, 32, v140
	s_waitcnt lgkmcnt(0)
	v_ashrrev_i32_e32 v97, 31, v96
	v_readlane_b32 s60, v240, 5
	v_lshlrev_b64 v[98:99], 12, v[96:97]
	v_readlane_b32 s61, v240, 6
	v_lshlrev_b64 v[114:115], 11, v[96:97]
	v_lshl_add_u64 v[114:115], s[12:13], 0, v[114:115]
	v_lshl_add_u64 v[98:99], s[60:61], 0, v[98:99]
	v_lshl_add_u64 v[110:111], v[138:139], 2, v[98:99]
	v_lshl_add_u64 v[234:235], v[110:111], 0, v[232:233]
	global_load_dwordx4 v[98:101], v[234:235], off
	global_load_dwordx4 v[102:105], v[234:235], off offset:64
	global_load_dwordx4 v[106:109], v[234:235], off offset:128
	s_nop 0
	global_load_dwordx4 v[110:113], v[234:235], off offset:192
	v_lshl_add_u64 v[114:115], v[138:139], 1, v[114:115]
	v_readlane_b32 s62, v240, 7
	v_readlane_b32 s63, v240, 8
	s_waitcnt vmcnt(0)
	v_permlane16_swap_b32_e32 v98, v102
	v_permlane16_swap_b32_e32 v99, v103
	v_permlane16_swap_b32_e32 v100, v104
	v_permlane16_swap_b32_e32 v101, v105
	v_permlane16_swap_b32_e32 v106, v110
	v_permlane16_swap_b32_e32 v107, v111
	v_permlane16_swap_b32_e32 v108, v112
	v_permlane16_swap_b32_e32 v109, v113
	v_permlane32_swap_b32_e32 v98, v106
	v_permlane32_swap_b32_e32 v99, v107
	v_permlane32_swap_b32_e32 v100, v108
	v_permlane32_swap_b32_e32 v101, v109
	v_permlane32_swap_b32_e32 v102, v110
	v_permlane32_swap_b32_e32 v103, v111
	v_permlane32_swap_b32_e32 v104, v112
	v_permlane32_swap_b32_e32 v105, v113
	v_pk_add_f32 v[92:93], v[92:93], v[98:99]
	v_pk_add_f32 v[94:95], v[94:95], v[100:101]
	s_waitcnt vmcnt(1)
	v_pk_add_f32 v[98:99], v[86:87], v[108:109]
	v_pk_add_f32 v[86:87], v[84:85], v[106:107]
	v_pk_mul_f32 v[84:85], v[92:93], v[92:93]
	v_pk_add_f32 v[88:89], v[88:89], v[102:103]
	s_waitcnt vmcnt(0)
	v_pk_add_f32 v[100:101], v[82:83], v[112:113]
	v_pk_add_f32 v[102:103], v[80:81], v[110:111]
	v_pk_mul_f32 v[80:81], v[94:95], v[94:95]
	v_add_f32_e32 v83, v84, v85
	v_add_f32_e32 v80, v80, v83
	v_pk_mul_f32 v[106:107], v[88:89], v[88:89]
	v_add_f32_e32 v80, v81, v80
	v_pk_add_f32 v[90:91], v[90:91], v[104:105]
	v_add_f32_e32 v80, v106, v80
	v_pk_mul_f32 v[104:105], v[90:91], v[90:91]
	v_add_f32_e32 v80, v107, v80
	v_add_f32_e32 v80, v104, v80
	v_pk_mul_f32 v[110:111], v[86:87], v[86:87]
	v_add_f32_e32 v80, v105, v80
	v_add_f32_e32 v80, v110, v80
	v_pk_mul_f32 v[108:109], v[98:99], v[98:99]
	v_add_f32_e32 v80, v111, v80
	v_add_f32_e32 v80, v108, v80
	v_pk_mul_f32 v[116:117], v[102:103], v[102:103]
	v_add_f32_e32 v80, v109, v80
	v_add_f32_e32 v80, v116, v80
	v_pk_mul_f32 v[112:113], v[100:101], v[100:101]
	v_add_f32_e32 v80, v117, v80
	v_add_f32_e32 v80, v112, v80
	v_add_f32_e32 v80, v113, v80
	v_mov_b32_e32 v81, v80
	s_nop 1
	v_permlane16_swap_b32_e32 v80, v81
	v_cvt_pk_bf16_f32 v82, v92, v93
	v_cvt_pk_bf16_f32 v83, v94, v95
	v_cvt_pk_bf16_f32 v84, v88, v89
	v_cvt_pk_bf16_f32 v85, v90, v91
	s_waitcnt lgkmcnt(0)
	v_add_f32_e32 v80, v80, v81
	v_mov_b32_e32 v81, v80
	s_nop 1
	v_permlane32_swap_b32_e32 v80, v81
	v_cvt_pk_bf16_f32 v86, v86, v87
	v_cvt_pk_bf16_f32 v87, v98, v99
	v_cvt_pk_bf16_f32 v88, v102, v103
	v_cvt_pk_bf16_f32 v89, v100, v101
	s_nop 1
	v_permlane16_swap_b32_e32 v82, v86
	v_permlane16_swap_b32_e32 v83, v87
	v_permlane16_swap_b32_e32 v84, v88
	v_permlane16_swap_b32_e32 v85, v89
	v_permlane32_swap_b32_e32 v82, v86
	v_permlane32_swap_b32_e32 v83, v87
	v_permlane32_swap_b32_e32 v84, v88
	v_permlane32_swap_b32_e32 v85, v89
	v_lshl_add_u64 v[238:239], v[114:115], 0, v[236:237]
	global_store_dwordx4 v[238:239], v[82:85], off
	global_store_dwordx4 v[238:239], v[86:89], off offset:64
	s_and_saveexec_b64 s[4:5], s[6:7]
	s_cbranch_execz .LBB0_1379
	v_lshlrev_b64 v[82:83], 6, v[96:97]
	v_lshl_add_u64 v[82:83], s[14:15], 0, v[82:83]
	v_lshl_add_u64 v[82:83], s[30:31], 2, v[82:83]
	s_lshl_b32 s8, s46, 2
	v_lshl_add_u64 v[82:83], v[82:83], 0, s[8:9]
	s_waitcnt lgkmcnt(0)
	v_add_f32_e32 v80, v80, v81
	global_store_dword v[82:83], v80, off
.LBB0_1379:
	s_or_b64 exec, exec, s[4:5]
	v_or_b32_e32 v80, 48, v140
	s_waitcnt lgkmcnt(0)
	v_ashrrev_i32_e32 v81, 31, v80
	v_readlane_b32 s60, v240, 5
	v_lshlrev_b64 v[82:83], 12, v[80:81]
	v_readlane_b32 s61, v240, 6
	v_lshlrev_b64 v[98:99], 11, v[80:81]
	v_lshl_add_u64 v[98:99], s[12:13], 0, v[98:99]
	v_lshl_add_u64 v[82:83], s[60:61], 0, v[82:83]
	v_lshl_add_u64 v[94:95], v[138:139], 2, v[82:83]
	v_lshl_add_u64 v[234:235], v[94:95], 0, v[232:233]
	global_load_dwordx4 v[82:85], v[234:235], off
	global_load_dwordx4 v[86:89], v[234:235], off offset:64
	global_load_dwordx4 v[90:93], v[234:235], off offset:128
	s_nop 0
	global_load_dwordx4 v[94:97], v[234:235], off offset:192
	v_lshl_add_u64 v[98:99], v[138:139], 1, v[98:99]
	v_readlane_b32 s62, v240, 7
	v_readlane_b32 s63, v240, 8
	s_waitcnt vmcnt(0)
	v_permlane16_swap_b32_e32 v82, v86
	v_permlane16_swap_b32_e32 v83, v87
	v_permlane16_swap_b32_e32 v84, v88
	v_permlane16_swap_b32_e32 v85, v89
	v_permlane16_swap_b32_e32 v90, v94
	v_permlane16_swap_b32_e32 v91, v95
	v_permlane16_swap_b32_e32 v92, v96
	v_permlane16_swap_b32_e32 v93, v97
	v_permlane32_swap_b32_e32 v82, v90
	v_permlane32_swap_b32_e32 v83, v91
	v_permlane32_swap_b32_e32 v84, v92
	v_permlane32_swap_b32_e32 v85, v93
	v_permlane32_swap_b32_e32 v86, v94
	v_permlane32_swap_b32_e32 v87, v95
	v_permlane32_swap_b32_e32 v88, v96
	v_permlane32_swap_b32_e32 v89, v97
	v_pk_add_f32 v[76:77], v[76:77], v[82:83]
	v_pk_add_f32 v[78:79], v[78:79], v[84:85]
	s_waitcnt vmcnt(1)
	v_pk_add_f32 v[82:83], v[70:71], v[92:93]
	v_pk_add_f32 v[70:71], v[68:69], v[90:91]
	v_pk_mul_f32 v[68:69], v[76:77], v[76:77]
	v_pk_add_f32 v[72:73], v[72:73], v[86:87]
	s_waitcnt vmcnt(0)
	v_pk_add_f32 v[84:85], v[66:67], v[96:97]
	v_pk_add_f32 v[86:87], v[64:65], v[94:95]
	v_pk_mul_f32 v[64:65], v[78:79], v[78:79]
	v_add_f32_e32 v67, v68, v69
	v_add_f32_e32 v64, v64, v67
	v_pk_mul_f32 v[90:91], v[72:73], v[72:73]
	v_add_f32_e32 v64, v65, v64
	v_pk_add_f32 v[74:75], v[74:75], v[88:89]
	v_add_f32_e32 v64, v90, v64
	v_pk_mul_f32 v[88:89], v[74:75], v[74:75]
	v_add_f32_e32 v64, v91, v64
	v_add_f32_e32 v64, v88, v64
	v_pk_mul_f32 v[94:95], v[70:71], v[70:71]
	v_add_f32_e32 v64, v89, v64
	v_add_f32_e32 v64, v94, v64
	v_pk_mul_f32 v[92:93], v[82:83], v[82:83]
	v_add_f32_e32 v64, v95, v64
	v_add_f32_e32 v64, v92, v64
	v_pk_mul_f32 v[100:101], v[86:87], v[86:87]
	v_add_f32_e32 v64, v93, v64
	v_add_f32_e32 v64, v100, v64
	v_pk_mul_f32 v[96:97], v[84:85], v[84:85]
	v_add_f32_e32 v64, v101, v64
	v_add_f32_e32 v64, v96, v64
	v_add_f32_e32 v64, v97, v64
	v_mov_b32_e32 v65, v64
	s_nop 1
	v_permlane16_swap_b32_e32 v64, v65
	v_cvt_pk_bf16_f32 v66, v76, v77
	v_cvt_pk_bf16_f32 v67, v78, v79
	v_cvt_pk_bf16_f32 v68, v72, v73
	v_cvt_pk_bf16_f32 v69, v74, v75
	s_waitcnt lgkmcnt(0)
	v_add_f32_e32 v64, v64, v65
	v_mov_b32_e32 v65, v64
	s_nop 1
	v_permlane32_swap_b32_e32 v64, v65
	v_cvt_pk_bf16_f32 v70, v70, v71
	v_cvt_pk_bf16_f32 v71, v82, v83
	v_cvt_pk_bf16_f32 v72, v86, v87
	v_cvt_pk_bf16_f32 v73, v84, v85
	s_nop 1
	v_permlane16_swap_b32_e32 v66, v70
	v_permlane16_swap_b32_e32 v67, v71
	v_permlane16_swap_b32_e32 v68, v72
	v_permlane16_swap_b32_e32 v69, v73
	v_permlane32_swap_b32_e32 v66, v70
	v_permlane32_swap_b32_e32 v67, v71
	v_permlane32_swap_b32_e32 v68, v72
	v_permlane32_swap_b32_e32 v69, v73
	v_lshl_add_u64 v[238:239], v[98:99], 0, v[236:237]
	global_store_dwordx4 v[238:239], v[66:69], off
	global_store_dwordx4 v[238:239], v[70:73], off offset:64
	s_and_saveexec_b64 s[4:5], s[6:7]
	s_cbranch_execz .LBB0_1381
	v_lshlrev_b64 v[66:67], 6, v[80:81]
	v_lshl_add_u64 v[66:67], s[14:15], 0, v[66:67]
	v_lshl_add_u64 v[66:67], s[30:31], 2, v[66:67]
	s_lshl_b32 s8, s46, 2
	v_lshl_add_u64 v[66:67], v[66:67], 0, s[8:9]
	s_waitcnt lgkmcnt(0)
	v_add_f32_e32 v64, v64, v65
	global_store_dword v[66:67], v64, off
.LBB0_1381:
	s_or_b64 exec, exec, s[4:5]
	v_add_u32_e32 v64, 0x80, v140
	s_waitcnt lgkmcnt(0)
	v_ashrrev_i32_e32 v65, 31, v64
	v_readlane_b32 s60, v240, 5
	v_lshlrev_b64 v[66:67], 12, v[64:65]
	v_readlane_b32 s61, v240, 6
	v_lshlrev_b64 v[82:83], 11, v[64:65]
	v_lshl_add_u64 v[82:83], s[12:13], 0, v[82:83]
	v_lshl_add_u64 v[66:67], s[60:61], 0, v[66:67]
	v_lshl_add_u64 v[78:79], v[138:139], 2, v[66:67]
	v_lshl_add_u64 v[234:235], v[78:79], 0, v[232:233]
	global_load_dwordx4 v[66:69], v[234:235], off
	global_load_dwordx4 v[70:73], v[234:235], off offset:64
	global_load_dwordx4 v[74:77], v[234:235], off offset:128
	s_nop 0
	global_load_dwordx4 v[78:81], v[234:235], off offset:192
	v_lshl_add_u64 v[82:83], v[138:139], 1, v[82:83]
	v_readlane_b32 s62, v240, 7
	v_readlane_b32 s63, v240, 8
	s_waitcnt vmcnt(0)
	v_permlane16_swap_b32_e32 v66, v70
	v_permlane16_swap_b32_e32 v67, v71
	v_permlane16_swap_b32_e32 v68, v72
	v_permlane16_swap_b32_e32 v69, v73
	v_permlane16_swap_b32_e32 v74, v78
	v_permlane16_swap_b32_e32 v75, v79
	v_permlane16_swap_b32_e32 v76, v80
	v_permlane16_swap_b32_e32 v77, v81
	v_permlane32_swap_b32_e32 v66, v74
	v_permlane32_swap_b32_e32 v67, v75
	v_permlane32_swap_b32_e32 v68, v76
	v_permlane32_swap_b32_e32 v69, v77
	v_permlane32_swap_b32_e32 v70, v78
	v_permlane32_swap_b32_e32 v71, v79
	v_permlane32_swap_b32_e32 v72, v80
	v_permlane32_swap_b32_e32 v73, v81
	v_pk_add_f32 v[60:61], v[60:61], v[66:67]
	v_pk_add_f32 v[62:63], v[62:63], v[68:69]
	s_waitcnt vmcnt(1)
	v_pk_add_f32 v[66:67], v[54:55], v[76:77]
	v_pk_add_f32 v[54:55], v[52:53], v[74:75]
	v_pk_mul_f32 v[52:53], v[60:61], v[60:61]
	v_pk_add_f32 v[56:57], v[56:57], v[70:71]
	s_waitcnt vmcnt(0)
	v_pk_add_f32 v[68:69], v[50:51], v[80:81]
	v_pk_add_f32 v[70:71], v[48:49], v[78:79]
	v_pk_mul_f32 v[48:49], v[62:63], v[62:63]
	v_add_f32_e32 v51, v52, v53
	v_add_f32_e32 v48, v48, v51
	v_pk_mul_f32 v[74:75], v[56:57], v[56:57]
	v_add_f32_e32 v48, v49, v48
	v_pk_add_f32 v[58:59], v[58:59], v[72:73]
	v_add_f32_e32 v48, v74, v48
	v_pk_mul_f32 v[72:73], v[58:59], v[58:59]
	v_add_f32_e32 v48, v75, v48
	v_add_f32_e32 v48, v72, v48
	v_pk_mul_f32 v[78:79], v[54:55], v[54:55]
	v_add_f32_e32 v48, v73, v48
	v_add_f32_e32 v48, v78, v48
	v_pk_mul_f32 v[76:77], v[66:67], v[66:67]
	v_add_f32_e32 v48, v79, v48
	v_add_f32_e32 v48, v76, v48
	v_pk_mul_f32 v[84:85], v[70:71], v[70:71]
	v_add_f32_e32 v48, v77, v48
	v_add_f32_e32 v48, v84, v48
	v_pk_mul_f32 v[80:81], v[68:69], v[68:69]
	v_add_f32_e32 v48, v85, v48
	v_add_f32_e32 v48, v80, v48
	v_add_f32_e32 v48, v81, v48
	v_mov_b32_e32 v49, v48
	s_nop 1
	v_permlane16_swap_b32_e32 v48, v49
	v_cvt_pk_bf16_f32 v50, v60, v61
	v_cvt_pk_bf16_f32 v51, v62, v63
	v_cvt_pk_bf16_f32 v52, v56, v57
	v_cvt_pk_bf16_f32 v53, v58, v59
	s_waitcnt lgkmcnt(0)
	v_add_f32_e32 v48, v48, v49
	v_mov_b32_e32 v49, v48
	s_nop 1
	v_permlane32_swap_b32_e32 v48, v49
	v_cvt_pk_bf16_f32 v54, v54, v55
	v_cvt_pk_bf16_f32 v55, v66, v67
	v_cvt_pk_bf16_f32 v56, v70, v71
	v_cvt_pk_bf16_f32 v57, v68, v69
	s_nop 1
	v_permlane16_swap_b32_e32 v50, v54
	v_permlane16_swap_b32_e32 v51, v55
	v_permlane16_swap_b32_e32 v52, v56
	v_permlane16_swap_b32_e32 v53, v57
	v_permlane32_swap_b32_e32 v50, v54
	v_permlane32_swap_b32_e32 v51, v55
	v_permlane32_swap_b32_e32 v52, v56
	v_permlane32_swap_b32_e32 v53, v57
	v_lshl_add_u64 v[238:239], v[82:83], 0, v[236:237]
	global_store_dwordx4 v[238:239], v[50:53], off
	global_store_dwordx4 v[238:239], v[54:57], off offset:64
	s_and_saveexec_b64 s[4:5], s[6:7]
	s_cbranch_execz .LBB0_1383
	v_lshlrev_b64 v[50:51], 6, v[64:65]
	v_lshl_add_u64 v[50:51], s[14:15], 0, v[50:51]
	v_lshl_add_u64 v[50:51], s[30:31], 2, v[50:51]
	s_lshl_b32 s8, s46, 2
	v_lshl_add_u64 v[50:51], v[50:51], 0, s[8:9]
	s_waitcnt lgkmcnt(0)
	v_add_f32_e32 v48, v48, v49
	global_store_dword v[50:51], v48, off
.LBB0_1383:
	s_or_b64 exec, exec, s[4:5]
	v_add_u32_e32 v48, 0x90, v140
	s_waitcnt lgkmcnt(0)
	v_ashrrev_i32_e32 v49, 31, v48
	v_readlane_b32 s60, v240, 5
	v_lshlrev_b64 v[50:51], 12, v[48:49]
	v_readlane_b32 s61, v240, 6
	v_lshlrev_b64 v[66:67], 11, v[48:49]
	v_lshl_add_u64 v[66:67], s[12:13], 0, v[66:67]
	v_lshl_add_u64 v[50:51], s[60:61], 0, v[50:51]
	v_lshl_add_u64 v[62:63], v[138:139], 2, v[50:51]
	v_lshl_add_u64 v[234:235], v[62:63], 0, v[232:233]
	global_load_dwordx4 v[50:53], v[234:235], off
	global_load_dwordx4 v[54:57], v[234:235], off offset:64
	global_load_dwordx4 v[58:61], v[234:235], off offset:128
	s_nop 0
	global_load_dwordx4 v[62:65], v[234:235], off offset:192
	v_lshl_add_u64 v[66:67], v[138:139], 1, v[66:67]
	v_readlane_b32 s62, v240, 7
	v_readlane_b32 s63, v240, 8
	s_waitcnt vmcnt(0)
	v_permlane16_swap_b32_e32 v50, v54
	v_permlane16_swap_b32_e32 v51, v55
	v_permlane16_swap_b32_e32 v52, v56
	v_permlane16_swap_b32_e32 v53, v57
	v_permlane16_swap_b32_e32 v58, v62
	v_permlane16_swap_b32_e32 v59, v63
	v_permlane16_swap_b32_e32 v60, v64
	v_permlane16_swap_b32_e32 v61, v65
	v_permlane32_swap_b32_e32 v50, v58
	v_permlane32_swap_b32_e32 v51, v59
	v_permlane32_swap_b32_e32 v52, v60
	v_permlane32_swap_b32_e32 v53, v61
	v_permlane32_swap_b32_e32 v54, v62
	v_permlane32_swap_b32_e32 v55, v63
	v_permlane32_swap_b32_e32 v56, v64
	v_permlane32_swap_b32_e32 v57, v65
	v_pk_add_f32 v[44:45], v[44:45], v[50:51]
	v_pk_add_f32 v[46:47], v[46:47], v[52:53]
	s_waitcnt vmcnt(1)
	v_pk_add_f32 v[50:51], v[38:39], v[60:61]
	v_pk_add_f32 v[38:39], v[36:37], v[58:59]
	v_pk_mul_f32 v[36:37], v[44:45], v[44:45]
	v_pk_add_f32 v[40:41], v[40:41], v[54:55]
	s_waitcnt vmcnt(0)
	v_pk_add_f32 v[52:53], v[34:35], v[64:65]
	v_pk_add_f32 v[54:55], v[32:33], v[62:63]
	v_pk_mul_f32 v[32:33], v[46:47], v[46:47]
	v_add_f32_e32 v35, v36, v37
	v_add_f32_e32 v32, v32, v35
	v_pk_mul_f32 v[58:59], v[40:41], v[40:41]
	v_add_f32_e32 v32, v33, v32
	v_pk_add_f32 v[42:43], v[42:43], v[56:57]
	v_add_f32_e32 v32, v58, v32
	v_pk_mul_f32 v[56:57], v[42:43], v[42:43]
	v_add_f32_e32 v32, v59, v32
	v_add_f32_e32 v32, v56, v32
	v_pk_mul_f32 v[62:63], v[38:39], v[38:39]
	v_add_f32_e32 v32, v57, v32
	v_add_f32_e32 v32, v62, v32
	v_pk_mul_f32 v[60:61], v[50:51], v[50:51]
	v_add_f32_e32 v32, v63, v32
	v_add_f32_e32 v32, v60, v32
	v_pk_mul_f32 v[68:69], v[54:55], v[54:55]
	v_add_f32_e32 v32, v61, v32
	v_add_f32_e32 v32, v68, v32
	v_pk_mul_f32 v[64:65], v[52:53], v[52:53]
	v_add_f32_e32 v32, v69, v32
	v_add_f32_e32 v32, v64, v32
	v_add_f32_e32 v32, v65, v32
	v_mov_b32_e32 v33, v32
	s_nop 1
	v_permlane16_swap_b32_e32 v32, v33
	v_cvt_pk_bf16_f32 v34, v44, v45
	v_cvt_pk_bf16_f32 v35, v46, v47
	v_cvt_pk_bf16_f32 v36, v40, v41
	v_cvt_pk_bf16_f32 v37, v42, v43
	s_waitcnt lgkmcnt(0)
	v_add_f32_e32 v32, v32, v33
	v_mov_b32_e32 v33, v32
	s_nop 1
	v_permlane32_swap_b32_e32 v32, v33
	v_cvt_pk_bf16_f32 v38, v38, v39
	v_cvt_pk_bf16_f32 v39, v50, v51
	v_cvt_pk_bf16_f32 v40, v54, v55
	v_cvt_pk_bf16_f32 v41, v52, v53
	s_nop 1
	v_permlane16_swap_b32_e32 v34, v38
	v_permlane16_swap_b32_e32 v35, v39
	v_permlane16_swap_b32_e32 v36, v40
	v_permlane16_swap_b32_e32 v37, v41
	v_permlane32_swap_b32_e32 v34, v38
	v_permlane32_swap_b32_e32 v35, v39
	v_permlane32_swap_b32_e32 v36, v40
	v_permlane32_swap_b32_e32 v37, v41
	v_lshl_add_u64 v[238:239], v[66:67], 0, v[236:237]
	global_store_dwordx4 v[238:239], v[34:37], off
	global_store_dwordx4 v[238:239], v[38:41], off offset:64
	s_and_saveexec_b64 s[4:5], s[6:7]
	s_cbranch_execz .LBB0_1385
	v_lshlrev_b64 v[34:35], 6, v[48:49]
	v_lshl_add_u64 v[34:35], s[14:15], 0, v[34:35]
	v_lshl_add_u64 v[34:35], s[30:31], 2, v[34:35]
	s_lshl_b32 s8, s46, 2
	v_lshl_add_u64 v[34:35], v[34:35], 0, s[8:9]
	s_waitcnt lgkmcnt(0)
	v_add_f32_e32 v32, v32, v33
	global_store_dword v[34:35], v32, off
.LBB0_1385:
	s_or_b64 exec, exec, s[4:5]
	v_add_u32_e32 v32, 0xa0, v140
	s_waitcnt lgkmcnt(0)
	v_ashrrev_i32_e32 v33, 31, v32
	v_readlane_b32 s60, v240, 5
	v_lshlrev_b64 v[34:35], 12, v[32:33]
	v_readlane_b32 s61, v240, 6
	v_lshlrev_b64 v[50:51], 11, v[32:33]
	v_lshl_add_u64 v[50:51], s[12:13], 0, v[50:51]
	v_lshl_add_u64 v[34:35], s[60:61], 0, v[34:35]
	v_lshl_add_u64 v[46:47], v[138:139], 2, v[34:35]
	v_lshl_add_u64 v[234:235], v[46:47], 0, v[232:233]
	global_load_dwordx4 v[34:37], v[234:235], off
	global_load_dwordx4 v[38:41], v[234:235], off offset:64
	global_load_dwordx4 v[42:45], v[234:235], off offset:128
	s_nop 0
	global_load_dwordx4 v[46:49], v[234:235], off offset:192
	v_lshl_add_u64 v[50:51], v[138:139], 1, v[50:51]
	v_readlane_b32 s62, v240, 7
	v_readlane_b32 s63, v240, 8
	s_waitcnt vmcnt(0)
	v_permlane16_swap_b32_e32 v34, v38
	v_permlane16_swap_b32_e32 v35, v39
	v_permlane16_swap_b32_e32 v36, v40
	v_permlane16_swap_b32_e32 v37, v41
	v_permlane16_swap_b32_e32 v42, v46
	v_permlane16_swap_b32_e32 v43, v47
	v_permlane16_swap_b32_e32 v44, v48
	v_permlane16_swap_b32_e32 v45, v49
	v_permlane32_swap_b32_e32 v34, v42
	v_permlane32_swap_b32_e32 v35, v43
	v_permlane32_swap_b32_e32 v36, v44
	v_permlane32_swap_b32_e32 v37, v45
	v_permlane32_swap_b32_e32 v38, v46
	v_permlane32_swap_b32_e32 v39, v47
	v_permlane32_swap_b32_e32 v40, v48
	v_permlane32_swap_b32_e32 v41, v49
	v_pk_add_f32 v[28:29], v[28:29], v[34:35]
	v_pk_add_f32 v[30:31], v[30:31], v[36:37]
	s_waitcnt vmcnt(1)
	v_pk_add_f32 v[34:35], v[22:23], v[44:45]
	v_pk_add_f32 v[22:23], v[20:21], v[42:43]
	v_pk_mul_f32 v[20:21], v[28:29], v[28:29]
	v_pk_add_f32 v[24:25], v[24:25], v[38:39]
	s_waitcnt vmcnt(0)
	v_pk_add_f32 v[36:37], v[18:19], v[48:49]
	v_pk_add_f32 v[38:39], v[16:17], v[46:47]
	v_pk_mul_f32 v[16:17], v[30:31], v[30:31]
	v_add_f32_e32 v19, v20, v21
	v_add_f32_e32 v16, v16, v19
	v_pk_mul_f32 v[42:43], v[24:25], v[24:25]
	v_add_f32_e32 v16, v17, v16
	v_pk_add_f32 v[26:27], v[26:27], v[40:41]
	v_add_f32_e32 v16, v42, v16
	v_pk_mul_f32 v[40:41], v[26:27], v[26:27]
	v_add_f32_e32 v16, v43, v16
	v_add_f32_e32 v16, v40, v16
	v_pk_mul_f32 v[46:47], v[22:23], v[22:23]
	v_add_f32_e32 v16, v41, v16
	v_add_f32_e32 v16, v46, v16
	v_pk_mul_f32 v[44:45], v[34:35], v[34:35]
	v_add_f32_e32 v16, v47, v16
	v_add_f32_e32 v16, v44, v16
	v_pk_mul_f32 v[52:53], v[38:39], v[38:39]
	v_add_f32_e32 v16, v45, v16
	v_add_f32_e32 v16, v52, v16
	v_pk_mul_f32 v[48:49], v[36:37], v[36:37]
	v_add_f32_e32 v16, v53, v16
	v_add_f32_e32 v16, v48, v16
	v_add_f32_e32 v16, v49, v16
	v_mov_b32_e32 v17, v16
	s_nop 1
	v_permlane16_swap_b32_e32 v16, v17
	v_cvt_pk_bf16_f32 v18, v28, v29
	v_cvt_pk_bf16_f32 v19, v30, v31
	v_cvt_pk_bf16_f32 v20, v24, v25
	v_cvt_pk_bf16_f32 v21, v26, v27
	s_waitcnt lgkmcnt(0)
	v_add_f32_e32 v16, v16, v17
	v_mov_b32_e32 v17, v16
	s_nop 1
	v_permlane32_swap_b32_e32 v16, v17
	v_cvt_pk_bf16_f32 v22, v22, v23
	v_cvt_pk_bf16_f32 v23, v34, v35
	v_cvt_pk_bf16_f32 v24, v38, v39
	v_cvt_pk_bf16_f32 v25, v36, v37
	s_nop 1
	v_permlane16_swap_b32_e32 v18, v22
	v_permlane16_swap_b32_e32 v19, v23
	v_permlane16_swap_b32_e32 v20, v24
	v_permlane16_swap_b32_e32 v21, v25
	v_permlane32_swap_b32_e32 v18, v22
	v_permlane32_swap_b32_e32 v19, v23
	v_permlane32_swap_b32_e32 v20, v24
	v_permlane32_swap_b32_e32 v21, v25
	v_lshl_add_u64 v[238:239], v[50:51], 0, v[236:237]
	global_store_dwordx4 v[238:239], v[18:21], off
	global_store_dwordx4 v[238:239], v[22:25], off offset:64
	s_and_saveexec_b64 s[4:5], s[6:7]
	s_cbranch_execz .LBB0_1387
	v_lshlrev_b64 v[18:19], 6, v[32:33]
	v_lshl_add_u64 v[18:19], s[14:15], 0, v[18:19]
	v_lshl_add_u64 v[18:19], s[30:31], 2, v[18:19]
	s_lshl_b32 s8, s46, 2
	v_lshl_add_u64 v[18:19], v[18:19], 0, s[8:9]
	s_waitcnt lgkmcnt(0)
	v_add_f32_e32 v16, v16, v17
	global_store_dword v[18:19], v16, off
.LBB0_1387:
	s_or_b64 exec, exec, s[4:5]
	v_add_u32_e32 v16, 0xb0, v140
	s_waitcnt lgkmcnt(0)
	v_ashrrev_i32_e32 v17, 31, v16
	v_readlane_b32 s60, v240, 5
	v_lshlrev_b64 v[18:19], 12, v[16:17]
	v_readlane_b32 s61, v240, 6
	v_lshlrev_b64 v[34:35], 11, v[16:17]
	v_lshl_add_u64 v[34:35], s[12:13], 0, v[34:35]
	v_lshl_add_u64 v[18:19], s[60:61], 0, v[18:19]
	v_lshl_add_u64 v[30:31], v[138:139], 2, v[18:19]
	v_lshl_add_u64 v[234:235], v[30:31], 0, v[232:233]
	global_load_dwordx4 v[18:21], v[234:235], off
	global_load_dwordx4 v[22:25], v[234:235], off offset:64
	global_load_dwordx4 v[26:29], v[234:235], off offset:128
	s_nop 0
	global_load_dwordx4 v[30:33], v[234:235], off offset:192
	v_lshl_add_u64 v[34:35], v[138:139], 1, v[34:35]
	v_readlane_b32 s62, v240, 7
	v_readlane_b32 s63, v240, 8
	s_waitcnt vmcnt(0)
	v_permlane16_swap_b32_e32 v18, v22
	v_permlane16_swap_b32_e32 v19, v23
	v_permlane16_swap_b32_e32 v20, v24
	v_permlane16_swap_b32_e32 v21, v25
	v_permlane16_swap_b32_e32 v26, v30
	v_permlane16_swap_b32_e32 v27, v31
	v_permlane16_swap_b32_e32 v28, v32
	v_permlane16_swap_b32_e32 v29, v33
	v_permlane32_swap_b32_e32 v18, v26
	v_permlane32_swap_b32_e32 v19, v27
	v_permlane32_swap_b32_e32 v20, v28
	v_permlane32_swap_b32_e32 v21, v29
	v_permlane32_swap_b32_e32 v22, v30
	v_permlane32_swap_b32_e32 v23, v31
	v_permlane32_swap_b32_e32 v24, v32
	v_permlane32_swap_b32_e32 v25, v33
	v_pk_add_f32 v[12:13], v[12:13], v[18:19]
	v_pk_add_f32 v[14:15], v[14:15], v[20:21]
	s_waitcnt vmcnt(1)
	v_pk_add_f32 v[18:19], v[6:7], v[28:29]
	v_pk_add_f32 v[6:7], v[4:5], v[26:27]
	v_pk_mul_f32 v[4:5], v[12:13], v[12:13]
	v_pk_add_f32 v[8:9], v[8:9], v[22:23]
	s_waitcnt vmcnt(0)
	v_pk_add_f32 v[20:21], v[2:3], v[32:33]
	v_pk_add_f32 v[22:23], v[0:1], v[30:31]
	v_pk_mul_f32 v[0:1], v[14:15], v[14:15]
	v_add_f32_e32 v3, v4, v5
	v_add_f32_e32 v0, v0, v3
	v_pk_mul_f32 v[26:27], v[8:9], v[8:9]
	v_add_f32_e32 v0, v1, v0
	v_pk_add_f32 v[10:11], v[10:11], v[24:25]
	v_add_f32_e32 v0, v26, v0
	v_pk_mul_f32 v[24:25], v[10:11], v[10:11]
	v_add_f32_e32 v0, v27, v0
	v_add_f32_e32 v0, v24, v0
	v_pk_mul_f32 v[30:31], v[6:7], v[6:7]
	v_add_f32_e32 v0, v25, v0
	v_add_f32_e32 v0, v30, v0
	v_pk_mul_f32 v[28:29], v[18:19], v[18:19]
	v_add_f32_e32 v0, v31, v0
	v_add_f32_e32 v0, v28, v0
	v_pk_mul_f32 v[36:37], v[22:23], v[22:23]
	v_add_f32_e32 v0, v29, v0
	v_add_f32_e32 v0, v36, v0
	v_pk_mul_f32 v[32:33], v[20:21], v[20:21]
	v_add_f32_e32 v0, v37, v0
	v_add_f32_e32 v0, v32, v0
	v_add_f32_e32 v0, v33, v0
	v_mov_b32_e32 v1, v0
	s_nop 1
	v_permlane16_swap_b32_e32 v0, v1
	v_cvt_pk_bf16_f32 v2, v12, v13
	v_cvt_pk_bf16_f32 v3, v14, v15
	v_cvt_pk_bf16_f32 v4, v8, v9
	v_cvt_pk_bf16_f32 v5, v10, v11
	s_waitcnt lgkmcnt(0)
	v_add_f32_e32 v0, v0, v1
	v_mov_b32_e32 v1, v0
	s_nop 1
	v_permlane32_swap_b32_e32 v0, v1
	v_cvt_pk_bf16_f32 v6, v6, v7
	v_cvt_pk_bf16_f32 v7, v18, v19
	v_cvt_pk_bf16_f32 v8, v22, v23
	v_cvt_pk_bf16_f32 v9, v20, v21
	s_nop 1
	v_permlane16_swap_b32_e32 v2, v6
	v_permlane16_swap_b32_e32 v3, v7
	v_permlane16_swap_b32_e32 v4, v8
	v_permlane16_swap_b32_e32 v5, v9
	v_permlane32_swap_b32_e32 v2, v6
	v_permlane32_swap_b32_e32 v3, v7
	v_permlane32_swap_b32_e32 v4, v8
	v_permlane32_swap_b32_e32 v5, v9
	v_lshl_add_u64 v[238:239], v[34:35], 0, v[236:237]
	global_store_dwordx4 v[238:239], v[2:5], off
	global_store_dwordx4 v[238:239], v[6:9], off offset:64
	s_and_saveexec_b64 s[4:5], s[6:7]
	s_cbranch_execz .LBB0_1389
	v_lshlrev_b64 v[2:3], 6, v[16:17]
	v_lshl_add_u64 v[2:3], s[14:15], 0, v[2:3]
	v_lshl_add_u64 v[2:3], s[30:31], 2, v[2:3]
	s_lshl_b32 s8, s46, 2
	v_lshl_add_u64 v[2:3], v[2:3], 0, s[8:9]
	s_waitcnt lgkmcnt(0)
	v_add_f32_e32 v0, v0, v1
	global_store_dword v[2:3], v0, off

.LBB0_1555:
	v_and_b32_e32 v236, 48, v144
	v_sub_u32_e32 v236, 0, v236
	v_ashrrev_i32_e32 v237, 31, v236
	v_lshl_add_u32 v140, s55, 8, v142
	v_ashrrev_i32_e32 v141, 31, v140
	v_lshl_or_b32 v138, s8, 8, v144
	v_lshlrev_b64 v[150:151], 11, v[140:141]
	v_ashrrev_i32_e32 v139, 31, v138
	v_lshl_add_u64 v[150:151], s[12:13], 0, v[150:151]
	v_lshl_add_u64 v[160:161], v[138:139], 1, v[150:151]
	v_lshl_add_u64 v[234:235], v[160:161], 0, v[236:237]
	global_load_dwordx4 v[152:155], v[234:235], off
	global_load_dwordx4 v[156:159], v[234:235], off offset:64
	v_and_b32_e32 v150, 64, v148
	v_xor_b32_e32 v149, 16, v148
	v_add_u32_e32 v150, 64, v150
	v_cmp_lt_i32_e32 vcc, v149, v150
	v_xor_b32_e32 v151, 32, v148
	s_lshl_b32 s26, s8, 2
	v_cndmask_b32_e32 v149, v148, v149, vcc
	v_cmp_lt_i32_e32 vcc, v151, v150
	v_lshlrev_b32_e32 v150, 2, v149
	s_ashr_i32 s27, s26, 31
	v_cndmask_b32_e32 v151, v148, v151, vcc
	v_lshlrev_b32_e32 v149, 2, v151
	s_waitcnt vmcnt(0)
	v_permlane32_swap_b32_e32 v152, v156
	v_permlane32_swap_b32_e32 v153, v157
	v_permlane32_swap_b32_e32 v154, v158
	v_permlane32_swap_b32_e32 v155, v159
	v_permlane16_swap_b32_e32 v152, v156
	v_permlane16_swap_b32_e32 v153, v157
	v_permlane16_swap_b32_e32 v154, v158
	v_permlane16_swap_b32_e32 v155, v159
	v_lshlrev_b32_e32 v162, 16, v152
	v_and_b32_e32 v163, 0xffff0000, v152
	v_lshlrev_b32_e32 v152, 16, v153
	v_and_b32_e32 v153, 0xffff0000, v153
	v_lshlrev_b32_e32 v164, 16, v154
	v_and_b32_e32 v165, 0xffff0000, v154
	v_lshlrev_b32_e32 v154, 16, v155
	v_and_b32_e32 v155, 0xffff0000, v155
	v_lshlrev_b32_e32 v166, 16, v156
	v_and_b32_e32 v167, 0xffff0000, v156
	v_lshlrev_b32_e32 v156, 16, v157
	v_and_b32_e32 v157, 0xffff0000, v157
	v_lshlrev_b32_e32 v168, 16, v158
	v_and_b32_e32 v169, 0xffff0000, v158
	v_pk_add_f32 v[120:121], v[120:121], v[162:163]
	v_pk_add_f32 v[122:123], v[122:123], v[152:153]
	v_pk_add_f32 v[126:127], v[126:127], v[154:155]
	v_pk_add_f32 v[154:155], v[118:119], v[156:157]
	v_pk_add_f32 v[156:157], v[112:113], v[168:169]
	v_pk_mul_f32 v[112:113], v[120:121], v[120:121]
	v_pk_add_f32 v[152:153], v[116:117], v[166:167]
	v_pk_mul_f32 v[116:117], v[122:123], v[122:123]
	v_add_f32_e32 v112, v112, v113
	v_pk_add_f32 v[124:125], v[124:125], v[164:165]
	v_add_f32_e32 v112, v116, v112
	v_pk_mul_f32 v[118:119], v[124:125], v[124:125]
	v_add_f32_e32 v112, v117, v112
	v_add_f32_e32 v112, v118, v112
	v_pk_mul_f32 v[162:163], v[126:127], v[126:127]
	v_add_f32_e32 v112, v119, v112
	v_add_f32_e32 v112, v162, v112
	v_pk_mul_f32 v[164:165], v[152:153], v[152:153]
	v_add_f32_e32 v112, v163, v112
	v_add_f32_e32 v112, v164, v112
	v_pk_mul_f32 v[166:167], v[154:155], v[154:155]
	v_add_f32_e32 v112, v165, v112
	v_add_f32_e32 v112, v166, v112
	v_lshlrev_b32_e32 v158, 16, v159
	v_and_b32_e32 v159, 0xffff0000, v159
	v_pk_mul_f32 v[168:169], v[156:157], v[156:157]
	v_add_f32_e32 v112, v167, v112
	v_pk_add_f32 v[158:159], v[114:115], v[158:159]
	v_add_f32_e32 v112, v168, v112
	v_pk_mul_f32 v[170:171], v[158:159], v[158:159]
	v_add_f32_e32 v112, v169, v112
	v_add_f32_e32 v112, v170, v112
	v_add_f32_e32 v112, v171, v112
	v_mov_b32_e32 v113, v112
	s_nop 1
	v_permlane16_swap_b32_e32 v112, v113
	v_cvt_pk_bf16_f32 v114, v120, v121
	v_cvt_pk_bf16_f32 v115, v122, v123
	v_cvt_pk_bf16_f32 v116, v124, v125
	v_cvt_pk_bf16_f32 v117, v126, v127
	s_waitcnt lgkmcnt(0)
	v_add_f32_e32 v112, v112, v113
	v_mov_b32_e32 v113, v112
	s_nop 1
	v_permlane32_swap_b32_e32 v112, v113
	v_cvt_pk_bf16_f32 v118, v152, v153
	v_cvt_pk_bf16_f32 v119, v154, v155
	v_cvt_pk_bf16_f32 v120, v156, v157
	v_cvt_pk_bf16_f32 v121, v158, v159
	s_nop 1
	v_permlane16_swap_b32_e32 v114, v118
	v_permlane16_swap_b32_e32 v115, v119
	v_permlane16_swap_b32_e32 v116, v120
	v_permlane16_swap_b32_e32 v117, v121
	v_permlane32_swap_b32_e32 v114, v118
	v_permlane32_swap_b32_e32 v115, v119
	v_permlane32_swap_b32_e32 v116, v120
	v_permlane32_swap_b32_e32 v117, v121
	v_lshl_add_u64 v[238:239], v[160:161], 0, v[236:237]
	global_store_dwordx4 v[238:239], v[114:117], off
	global_store_dwordx4 v[238:239], v[118:121], off offset:64
	s_and_saveexec_b64 s[4:5], s[6:7]
	s_cbranch_execz .LBB0_1557
	s_waitcnt lgkmcnt(0)
	v_add_f32_e32 v114, v112, v113
	v_lshlrev_b64 v[112:113], 6, v[140:141]
	v_lshl_add_u64 v[112:113], s[14:15], 0, v[112:113]
	v_lshl_add_u64 v[112:113], s[26:27], 2, v[112:113]
	s_lshl_b32 s8, s40, 2
	v_lshl_add_u64 v[112:113], v[112:113], 0, s[8:9]
	global_store_dword v[112:113], v114, off
.LBB0_1557:
	s_or_b64 exec, exec, s[4:5]
	v_or_b32_e32 v112, 16, v140
	s_waitcnt lgkmcnt(0)
	v_ashrrev_i32_e32 v113, 31, v112
	v_lshlrev_b64 v[114:115], 11, v[112:113]
	v_lshl_add_u64 v[114:115], s[12:13], 0, v[114:115]
	v_lshl_add_u64 v[122:123], v[138:139], 1, v[114:115]
	v_lshl_add_u64 v[234:235], v[122:123], 0, v[236:237]
	global_load_dwordx4 v[114:117], v[234:235], off
	global_load_dwordx4 v[118:121], v[234:235], off offset:64
	s_waitcnt vmcnt(0)
	v_permlane32_swap_b32_e32 v114, v118
	v_permlane32_swap_b32_e32 v115, v119
	v_permlane32_swap_b32_e32 v116, v120
	v_permlane32_swap_b32_e32 v117, v121
	v_permlane16_swap_b32_e32 v114, v118
	v_permlane16_swap_b32_e32 v115, v119
	v_permlane16_swap_b32_e32 v116, v120
	v_permlane16_swap_b32_e32 v117, v121
	v_lshlrev_b32_e32 v124, 16, v114
	v_and_b32_e32 v125, 0xffff0000, v114
	v_lshlrev_b32_e32 v114, 16, v115
	v_and_b32_e32 v115, 0xffff0000, v115
	v_lshlrev_b32_e32 v126, 16, v116
	v_and_b32_e32 v127, 0xffff0000, v116
	v_lshlrev_b32_e32 v116, 16, v117
	v_and_b32_e32 v117, 0xffff0000, v117
	s_waitcnt vmcnt(0)
	v_lshlrev_b32_e32 v152, 16, v118
	v_and_b32_e32 v153, 0xffff0000, v118
	v_lshlrev_b32_e32 v118, 16, v119
	v_and_b32_e32 v119, 0xffff0000, v119
	v_lshlrev_b32_e32 v154, 16, v120
	v_and_b32_e32 v155, 0xffff0000, v120
	v_pk_add_f32 v[108:109], v[108:109], v[124:125]
	v_pk_add_f32 v[110:111], v[110:111], v[114:115]
	v_pk_add_f32 v[106:107], v[106:107], v[116:117]
	v_pk_add_f32 v[116:117], v[102:103], v[118:119]
	v_pk_add_f32 v[118:119], v[96:97], v[154:155]
	v_pk_mul_f32 v[96:97], v[108:109], v[108:109]
	v_pk_add_f32 v[114:115], v[100:101], v[152:153]
	v_pk_mul_f32 v[100:101], v[110:111], v[110:111]
	v_add_f32_e32 v96, v96, v97
	v_pk_add_f32 v[104:105], v[104:105], v[126:127]
	v_add_f32_e32 v96, v100, v96
	v_pk_mul_f32 v[102:103], v[104:105], v[104:105]
	v_add_f32_e32 v96, v101, v96
	v_add_f32_e32 v96, v102, v96
	v_pk_mul_f32 v[124:125], v[106:107], v[106:107]
	v_add_f32_e32 v96, v103, v96
	v_add_f32_e32 v96, v124, v96
	v_pk_mul_f32 v[126:127], v[114:115], v[114:115]
	v_add_f32_e32 v96, v125, v96
	v_add_f32_e32 v96, v126, v96
	v_pk_mul_f32 v[152:153], v[116:117], v[116:117]
	v_add_f32_e32 v96, v127, v96
	v_add_f32_e32 v96, v152, v96
	v_lshlrev_b32_e32 v120, 16, v121
	v_and_b32_e32 v121, 0xffff0000, v121
	v_pk_mul_f32 v[154:155], v[118:119], v[118:119]
	v_add_f32_e32 v96, v153, v96
	v_pk_add_f32 v[120:121], v[98:99], v[120:121]
	v_add_f32_e32 v96, v154, v96
	v_pk_mul_f32 v[156:157], v[120:121], v[120:121]
	v_add_f32_e32 v96, v155, v96
	v_add_f32_e32 v96, v156, v96
	v_add_f32_e32 v96, v157, v96
	v_mov_b32_e32 v97, v96
	s_nop 1
	v_permlane16_swap_b32_e32 v96, v97
	v_cvt_pk_bf16_f32 v98, v108, v109
	v_cvt_pk_bf16_f32 v99, v110, v111
	v_cvt_pk_bf16_f32 v100, v104, v105
	v_cvt_pk_bf16_f32 v101, v106, v107
	s_waitcnt lgkmcnt(0)
	v_add_f32_e32 v96, v96, v97
	v_mov_b32_e32 v97, v96
	s_nop 1
	v_permlane32_swap_b32_e32 v96, v97
	v_cvt_pk_bf16_f32 v102, v114, v115
	v_cvt_pk_bf16_f32 v103, v116, v117
	v_cvt_pk_bf16_f32 v104, v118, v119
	v_cvt_pk_bf16_f32 v105, v120, v121
	s_nop 1
	v_permlane16_swap_b32_e32 v98, v102
	v_permlane16_swap_b32_e32 v99, v103
	v_permlane16_swap_b32_e32 v100, v104
	v_permlane16_swap_b32_e32 v101, v105
	v_permlane32_swap_b32_e32 v98, v102
	v_permlane32_swap_b32_e32 v99, v103
	v_permlane32_swap_b32_e32 v100, v104
	v_permlane32_swap_b32_e32 v101, v105
	v_lshl_add_u64 v[238:239], v[122:123], 0, v[236:237]
	global_store_dwordx4 v[238:239], v[98:101], off
	global_store_dwordx4 v[238:239], v[102:105], off offset:64
	s_and_saveexec_b64 s[4:5], s[6:7]
	s_cbranch_execz .LBB0_1559
	s_waitcnt lgkmcnt(0)
	v_add_f32_e32 v98, v96, v97
	v_lshlrev_b64 v[96:97], 6, v[112:113]
	v_lshl_add_u64 v[96:97], s[14:15], 0, v[96:97]
	v_lshl_add_u64 v[96:97], s[26:27], 2, v[96:97]
	s_lshl_b32 s8, s40, 2
	v_lshl_add_u64 v[96:97], v[96:97], 0, s[8:9]
	global_store_dword v[96:97], v98, off
.LBB0_1559:
	s_or_b64 exec, exec, s[4:5]
	v_or_b32_e32 v96, 32, v140
	s_waitcnt lgkmcnt(0)
	v_ashrrev_i32_e32 v97, 31, v96
	v_lshlrev_b64 v[98:99], 11, v[96:97]
	v_lshl_add_u64 v[98:99], s[12:13], 0, v[98:99]
	v_lshl_add_u64 v[106:107], v[138:139], 1, v[98:99]
	v_lshl_add_u64 v[234:235], v[106:107], 0, v[236:237]
	global_load_dwordx4 v[98:101], v[234:235], off
	global_load_dwordx4 v[102:105], v[234:235], off offset:64
	s_waitcnt vmcnt(0)
	v_permlane32_swap_b32_e32 v98, v102
	v_permlane32_swap_b32_e32 v99, v103
	v_permlane32_swap_b32_e32 v100, v104
	v_permlane32_swap_b32_e32 v101, v105
	v_permlane16_swap_b32_e32 v98, v102
	v_permlane16_swap_b32_e32 v99, v103
	v_permlane16_swap_b32_e32 v100, v104
	v_permlane16_swap_b32_e32 v101, v105
	v_lshlrev_b32_e32 v108, 16, v98
	v_and_b32_e32 v109, 0xffff0000, v98
	v_lshlrev_b32_e32 v98, 16, v99
	v_and_b32_e32 v99, 0xffff0000, v99
	v_lshlrev_b32_e32 v110, 16, v100
	v_and_b32_e32 v111, 0xffff0000, v100
	v_lshlrev_b32_e32 v100, 16, v101
	v_and_b32_e32 v101, 0xffff0000, v101
	s_waitcnt vmcnt(0)
	v_lshlrev_b32_e32 v112, 16, v102
	v_and_b32_e32 v113, 0xffff0000, v102
	v_lshlrev_b32_e32 v102, 16, v103
	v_and_b32_e32 v103, 0xffff0000, v103
	v_lshlrev_b32_e32 v114, 16, v104
	v_and_b32_e32 v115, 0xffff0000, v104
	v_pk_add_f32 v[92:93], v[92:93], v[108:109]
	v_pk_add_f32 v[94:95], v[94:95], v[98:99]
	v_pk_add_f32 v[90:91], v[90:91], v[100:101]
	v_pk_add_f32 v[100:101], v[86:87], v[102:103]
	v_pk_add_f32 v[102:103], v[80:81], v[114:115]
	v_pk_mul_f32 v[80:81], v[92:93], v[92:93]
	v_pk_add_f32 v[98:99], v[84:85], v[112:113]
	v_pk_mul_f32 v[84:85], v[94:95], v[94:95]
	v_add_f32_e32 v80, v80, v81
	v_pk_add_f32 v[88:89], v[88:89], v[110:111]
	v_add_f32_e32 v80, v84, v80
	v_pk_mul_f32 v[86:87], v[88:89], v[88:89]
	v_add_f32_e32 v80, v85, v80
	v_add_f32_e32 v80, v86, v80
	v_pk_mul_f32 v[108:109], v[90:91], v[90:91]
	v_add_f32_e32 v80, v87, v80
	v_add_f32_e32 v80, v108, v80
	v_pk_mul_f32 v[110:111], v[98:99], v[98:99]
	v_add_f32_e32 v80, v109, v80
	v_add_f32_e32 v80, v110, v80
	v_pk_mul_f32 v[112:113], v[100:101], v[100:101]
	v_add_f32_e32 v80, v111, v80
	v_add_f32_e32 v80, v112, v80
	v_lshlrev_b32_e32 v104, 16, v105
	v_and_b32_e32 v105, 0xffff0000, v105
	v_pk_mul_f32 v[114:115], v[102:103], v[102:103]
	v_add_f32_e32 v80, v113, v80
	v_pk_add_f32 v[104:105], v[82:83], v[104:105]
	v_add_f32_e32 v80, v114, v80
	v_pk_mul_f32 v[116:117], v[104:105], v[104:105]
	v_add_f32_e32 v80, v115, v80
	v_add_f32_e32 v80, v116, v80
	v_add_f32_e32 v80, v117, v80
	v_mov_b32_e32 v81, v80
	s_nop 1
	v_permlane16_swap_b32_e32 v80, v81
	v_cvt_pk_bf16_f32 v82, v92, v93
	v_cvt_pk_bf16_f32 v83, v94, v95
	v_cvt_pk_bf16_f32 v84, v88, v89
	v_cvt_pk_bf16_f32 v85, v90, v91
	s_waitcnt lgkmcnt(0)
	v_add_f32_e32 v80, v80, v81
	v_mov_b32_e32 v81, v80
	s_nop 1
	v_permlane32_swap_b32_e32 v80, v81
	v_cvt_pk_bf16_f32 v86, v98, v99
	v_cvt_pk_bf16_f32 v87, v100, v101
	v_cvt_pk_bf16_f32 v88, v102, v103
	v_cvt_pk_bf16_f32 v89, v104, v105
	s_nop 1
	v_permlane16_swap_b32_e32 v82, v86
	v_permlane16_swap_b32_e32 v83, v87
	v_permlane16_swap_b32_e32 v84, v88
	v_permlane16_swap_b32_e32 v85, v89
	v_permlane32_swap_b32_e32 v82, v86
	v_permlane32_swap_b32_e32 v83, v87
	v_permlane32_swap_b32_e32 v84, v88
	v_permlane32_swap_b32_e32 v85, v89
	v_lshl_add_u64 v[238:239], v[106:107], 0, v[236:237]
	global_store_dwordx4 v[238:239], v[82:85], off
	global_store_dwordx4 v[238:239], v[86:89], off offset:64
	s_and_saveexec_b64 s[4:5], s[6:7]
	s_cbranch_execz .LBB0_1561
	s_waitcnt lgkmcnt(0)
	v_add_f32_e32 v82, v80, v81
	v_lshlrev_b64 v[80:81], 6, v[96:97]
	v_lshl_add_u64 v[80:81], s[14:15], 0, v[80:81]
	v_lshl_add_u64 v[80:81], s[26:27], 2, v[80:81]
	s_lshl_b32 s8, s40, 2
	v_lshl_add_u64 v[80:81], v[80:81], 0, s[8:9]
	global_store_dword v[80:81], v82, off
.LBB0_1561:
	s_or_b64 exec, exec, s[4:5]
	v_or_b32_e32 v80, 48, v140
	s_waitcnt lgkmcnt(0)
	v_ashrrev_i32_e32 v81, 31, v80
	v_lshlrev_b64 v[82:83], 11, v[80:81]
	v_lshl_add_u64 v[82:83], s[12:13], 0, v[82:83]
	v_lshl_add_u64 v[90:91], v[138:139], 1, v[82:83]
	v_lshl_add_u64 v[234:235], v[90:91], 0, v[236:237]
	global_load_dwordx4 v[82:85], v[234:235], off
	global_load_dwordx4 v[86:89], v[234:235], off offset:64
	s_waitcnt vmcnt(0)
	v_permlane32_swap_b32_e32 v82, v86
	v_permlane32_swap_b32_e32 v83, v87
	v_permlane32_swap_b32_e32 v84, v88
	v_permlane32_swap_b32_e32 v85, v89
	v_permlane16_swap_b32_e32 v82, v86
	v_permlane16_swap_b32_e32 v83, v87
	v_permlane16_swap_b32_e32 v84, v88
	v_permlane16_swap_b32_e32 v85, v89
	v_lshlrev_b32_e32 v92, 16, v82
	v_and_b32_e32 v93, 0xffff0000, v82
	v_lshlrev_b32_e32 v82, 16, v83
	v_and_b32_e32 v83, 0xffff0000, v83
	v_lshlrev_b32_e32 v94, 16, v84
	v_and_b32_e32 v95, 0xffff0000, v84
	v_lshlrev_b32_e32 v84, 16, v85
	v_and_b32_e32 v85, 0xffff0000, v85
	s_waitcnt vmcnt(0)
	v_lshlrev_b32_e32 v96, 16, v86
	v_and_b32_e32 v97, 0xffff0000, v86
	v_lshlrev_b32_e32 v86, 16, v87
	v_and_b32_e32 v87, 0xffff0000, v87
	v_lshlrev_b32_e32 v98, 16, v88
	v_and_b32_e32 v99, 0xffff0000, v88
	v_pk_add_f32 v[76:77], v[76:77], v[92:93]
	v_pk_add_f32 v[78:79], v[78:79], v[82:83]
	v_pk_add_f32 v[74:75], v[74:75], v[84:85]
	v_pk_add_f32 v[84:85], v[70:71], v[86:87]
	v_pk_add_f32 v[86:87], v[64:65], v[98:99]
	v_pk_mul_f32 v[64:65], v[76:77], v[76:77]
	v_pk_add_f32 v[82:83], v[68:69], v[96:97]
	v_pk_mul_f32 v[68:69], v[78:79], v[78:79]
	v_add_f32_e32 v64, v64, v65
	v_pk_add_f32 v[72:73], v[72:73], v[94:95]
	v_add_f32_e32 v64, v68, v64
	v_pk_mul_f32 v[70:71], v[72:73], v[72:73]
	v_add_f32_e32 v64, v69, v64
	v_add_f32_e32 v64, v70, v64
	v_pk_mul_f32 v[92:93], v[74:75], v[74:75]
	v_add_f32_e32 v64, v71, v64
	v_add_f32_e32 v64, v92, v64
	v_pk_mul_f32 v[94:95], v[82:83], v[82:83]
	v_add_f32_e32 v64, v93, v64
	v_add_f32_e32 v64, v94, v64
	v_pk_mul_f32 v[96:97], v[84:85], v[84:85]
	v_add_f32_e32 v64, v95, v64
	v_add_f32_e32 v64, v96, v64
	v_lshlrev_b32_e32 v88, 16, v89
	v_and_b32_e32 v89, 0xffff0000, v89
	v_pk_mul_f32 v[98:99], v[86:87], v[86:87]
	v_add_f32_e32 v64, v97, v64
	v_pk_add_f32 v[88:89], v[66:67], v[88:89]
	v_add_f32_e32 v64, v98, v64
	v_pk_mul_f32 v[100:101], v[88:89], v[88:89]
	v_add_f32_e32 v64, v99, v64
	v_add_f32_e32 v64, v100, v64
	v_add_f32_e32 v64, v101, v64
	v_mov_b32_e32 v65, v64
	s_nop 1
	v_permlane16_swap_b32_e32 v64, v65
	v_cvt_pk_bf16_f32 v66, v76, v77
	v_cvt_pk_bf16_f32 v67, v78, v79
	v_cvt_pk_bf16_f32 v68, v72, v73
	v_cvt_pk_bf16_f32 v69, v74, v75
	s_waitcnt lgkmcnt(0)
	v_add_f32_e32 v64, v64, v65
	v_mov_b32_e32 v65, v64
	s_nop 1
	v_permlane32_swap_b32_e32 v64, v65
	v_cvt_pk_bf16_f32 v70, v82, v83
	v_cvt_pk_bf16_f32 v71, v84, v85
	v_cvt_pk_bf16_f32 v72, v86, v87
	v_cvt_pk_bf16_f32 v73, v88, v89
	s_nop 1
	v_permlane16_swap_b32_e32 v66, v70
	v_permlane16_swap_b32_e32 v67, v71
	v_permlane16_swap_b32_e32 v68, v72
	v_permlane16_swap_b32_e32 v69, v73
	v_permlane32_swap_b32_e32 v66, v70
	v_permlane32_swap_b32_e32 v67, v71
	v_permlane32_swap_b32_e32 v68, v72
	v_permlane32_swap_b32_e32 v69, v73
	v_lshl_add_u64 v[238:239], v[90:91], 0, v[236:237]
	global_store_dwordx4 v[238:239], v[66:69], off
	global_store_dwordx4 v[238:239], v[70:73], off offset:64
	s_and_saveexec_b64 s[4:5], s[6:7]
	s_cbranch_execz .LBB0_1563
	s_waitcnt lgkmcnt(0)
	v_add_f32_e32 v66, v64, v65
	v_lshlrev_b64 v[64:65], 6, v[80:81]
	v_lshl_add_u64 v[64:65], s[14:15], 0, v[64:65]
	v_lshl_add_u64 v[64:65], s[26:27], 2, v[64:65]
	s_lshl_b32 s8, s40, 2
	v_lshl_add_u64 v[64:65], v[64:65], 0, s[8:9]
	global_store_dword v[64:65], v66, off
.LBB0_1563:
	s_or_b64 exec, exec, s[4:5]
	v_add_u32_e32 v64, 0x80, v140
	s_waitcnt lgkmcnt(0)
	v_ashrrev_i32_e32 v65, 31, v64
	v_lshlrev_b64 v[66:67], 11, v[64:65]
	v_lshl_add_u64 v[66:67], s[12:13], 0, v[66:67]
	v_lshl_add_u64 v[74:75], v[138:139], 1, v[66:67]
	v_lshl_add_u64 v[234:235], v[74:75], 0, v[236:237]
	global_load_dwordx4 v[66:69], v[234:235], off
	global_load_dwordx4 v[70:73], v[234:235], off offset:64
	s_waitcnt vmcnt(0)
	v_permlane32_swap_b32_e32 v66, v70
	v_permlane32_swap_b32_e32 v67, v71
	v_permlane32_swap_b32_e32 v68, v72
	v_permlane32_swap_b32_e32 v69, v73
	v_permlane16_swap_b32_e32 v66, v70
	v_permlane16_swap_b32_e32 v67, v71
	v_permlane16_swap_b32_e32 v68, v72
	v_permlane16_swap_b32_e32 v69, v73
	v_lshlrev_b32_e32 v76, 16, v66
	v_and_b32_e32 v77, 0xffff0000, v66
	v_lshlrev_b32_e32 v66, 16, v67
	v_and_b32_e32 v67, 0xffff0000, v67
	v_lshlrev_b32_e32 v78, 16, v68
	v_and_b32_e32 v79, 0xffff0000, v68
	v_lshlrev_b32_e32 v68, 16, v69
	v_and_b32_e32 v69, 0xffff0000, v69
	s_waitcnt vmcnt(0)
	v_lshlrev_b32_e32 v80, 16, v70
	v_and_b32_e32 v81, 0xffff0000, v70
	v_lshlrev_b32_e32 v70, 16, v71
	v_and_b32_e32 v71, 0xffff0000, v71
	v_lshlrev_b32_e32 v82, 16, v72
	v_and_b32_e32 v83, 0xffff0000, v72
	v_pk_add_f32 v[60:61], v[60:61], v[76:77]
	v_pk_add_f32 v[62:63], v[62:63], v[66:67]
	v_pk_add_f32 v[58:59], v[58:59], v[68:69]
	v_pk_add_f32 v[68:69], v[54:55], v[70:71]
	v_pk_add_f32 v[70:71], v[48:49], v[82:83]
	v_pk_mul_f32 v[48:49], v[60:61], v[60:61]
	v_pk_add_f32 v[66:67], v[52:53], v[80:81]
	v_pk_mul_f32 v[52:53], v[62:63], v[62:63]
	v_add_f32_e32 v48, v48, v49
	v_pk_add_f32 v[56:57], v[56:57], v[78:79]
	v_add_f32_e32 v48, v52, v48
	v_pk_mul_f32 v[54:55], v[56:57], v[56:57]
	v_add_f32_e32 v48, v53, v48
	v_add_f32_e32 v48, v54, v48
	v_pk_mul_f32 v[76:77], v[58:59], v[58:59]
	v_add_f32_e32 v48, v55, v48
	v_add_f32_e32 v48, v76, v48
	v_pk_mul_f32 v[78:79], v[66:67], v[66:67]
	v_add_f32_e32 v48, v77, v48
	v_add_f32_e32 v48, v78, v48
	v_pk_mul_f32 v[80:81], v[68:69], v[68:69]
	v_add_f32_e32 v48, v79, v48
	v_add_f32_e32 v48, v80, v48
	v_lshlrev_b32_e32 v72, 16, v73
	v_and_b32_e32 v73, 0xffff0000, v73
	v_pk_mul_f32 v[82:83], v[70:71], v[70:71]
	v_add_f32_e32 v48, v81, v48
	v_pk_add_f32 v[72:73], v[50:51], v[72:73]
	v_add_f32_e32 v48, v82, v48
	v_pk_mul_f32 v[84:85], v[72:73], v[72:73]
	v_add_f32_e32 v48, v83, v48
	v_add_f32_e32 v48, v84, v48
	v_add_f32_e32 v48, v85, v48
	v_mov_b32_e32 v49, v48
	s_nop 1
	v_permlane16_swap_b32_e32 v48, v49
	v_cvt_pk_bf16_f32 v50, v60, v61
	v_cvt_pk_bf16_f32 v51, v62, v63
	v_cvt_pk_bf16_f32 v52, v56, v57
	v_cvt_pk_bf16_f32 v53, v58, v59
	s_waitcnt lgkmcnt(0)
	v_add_f32_e32 v48, v48, v49
	v_mov_b32_e32 v49, v48
	s_nop 1
	v_permlane32_swap_b32_e32 v48, v49
	v_cvt_pk_bf16_f32 v54, v66, v67
	v_cvt_pk_bf16_f32 v55, v68, v69
	v_cvt_pk_bf16_f32 v56, v70, v71
	v_cvt_pk_bf16_f32 v57, v72, v73
	s_nop 1
	v_permlane16_swap_b32_e32 v50, v54
	v_permlane16_swap_b32_e32 v51, v55
	v_permlane16_swap_b32_e32 v52, v56
	v_permlane16_swap_b32_e32 v53, v57
	v_permlane32_swap_b32_e32 v50, v54
	v_permlane32_swap_b32_e32 v51, v55
	v_permlane32_swap_b32_e32 v52, v56
	v_permlane32_swap_b32_e32 v53, v57
	v_lshl_add_u64 v[238:239], v[74:75], 0, v[236:237]
	global_store_dwordx4 v[238:239], v[50:53], off
	global_store_dwordx4 v[238:239], v[54:57], off offset:64
	s_and_saveexec_b64 s[4:5], s[6:7]
	s_cbranch_execz .LBB0_1565
	s_waitcnt lgkmcnt(0)
	v_add_f32_e32 v50, v48, v49
	v_lshlrev_b64 v[48:49], 6, v[64:65]
	v_lshl_add_u64 v[48:49], s[14:15], 0, v[48:49]
	v_lshl_add_u64 v[48:49], s[26:27], 2, v[48:49]
	s_lshl_b32 s8, s40, 2
	v_lshl_add_u64 v[48:49], v[48:49], 0, s[8:9]
	global_store_dword v[48:49], v50, off
.LBB0_1565:
	s_or_b64 exec, exec, s[4:5]
	v_add_u32_e32 v48, 0x90, v140
	s_waitcnt lgkmcnt(0)
	v_ashrrev_i32_e32 v49, 31, v48
	v_lshlrev_b64 v[50:51], 11, v[48:49]
	v_lshl_add_u64 v[50:51], s[12:13], 0, v[50:51]
	v_lshl_add_u64 v[58:59], v[138:139], 1, v[50:51]
	v_lshl_add_u64 v[234:235], v[58:59], 0, v[236:237]
	global_load_dwordx4 v[50:53], v[234:235], off
	global_load_dwordx4 v[54:57], v[234:235], off offset:64
	s_waitcnt vmcnt(0)
	v_permlane32_swap_b32_e32 v50, v54
	v_permlane32_swap_b32_e32 v51, v55
	v_permlane32_swap_b32_e32 v52, v56
	v_permlane32_swap_b32_e32 v53, v57
	v_permlane16_swap_b32_e32 v50, v54
	v_permlane16_swap_b32_e32 v51, v55
	v_permlane16_swap_b32_e32 v52, v56
	v_permlane16_swap_b32_e32 v53, v57
	v_lshlrev_b32_e32 v60, 16, v50
	v_and_b32_e32 v61, 0xffff0000, v50
	v_lshlrev_b32_e32 v50, 16, v51
	v_and_b32_e32 v51, 0xffff0000, v51
	v_lshlrev_b32_e32 v62, 16, v52
	v_and_b32_e32 v63, 0xffff0000, v52
	v_lshlrev_b32_e32 v52, 16, v53
	v_and_b32_e32 v53, 0xffff0000, v53
	s_waitcnt vmcnt(0)
	v_lshlrev_b32_e32 v64, 16, v54
	v_and_b32_e32 v65, 0xffff0000, v54
	v_lshlrev_b32_e32 v54, 16, v55
	v_and_b32_e32 v55, 0xffff0000, v55
	v_lshlrev_b32_e32 v66, 16, v56
	v_and_b32_e32 v67, 0xffff0000, v56
	v_pk_add_f32 v[44:45], v[44:45], v[60:61]
	v_pk_add_f32 v[46:47], v[46:47], v[50:51]
	v_pk_add_f32 v[42:43], v[42:43], v[52:53]
	v_pk_add_f32 v[52:53], v[38:39], v[54:55]
	v_pk_add_f32 v[54:55], v[32:33], v[66:67]
	v_pk_mul_f32 v[32:33], v[44:45], v[44:45]
	v_pk_add_f32 v[50:51], v[36:37], v[64:65]
	v_pk_mul_f32 v[36:37], v[46:47], v[46:47]
	v_add_f32_e32 v32, v32, v33
	v_pk_add_f32 v[40:41], v[40:41], v[62:63]
	v_add_f32_e32 v32, v36, v32
	v_pk_mul_f32 v[38:39], v[40:41], v[40:41]
	v_add_f32_e32 v32, v37, v32
	v_add_f32_e32 v32, v38, v32
	v_pk_mul_f32 v[60:61], v[42:43], v[42:43]
	v_add_f32_e32 v32, v39, v32
	v_add_f32_e32 v32, v60, v32
	v_pk_mul_f32 v[62:63], v[50:51], v[50:51]
	v_add_f32_e32 v32, v61, v32
	v_add_f32_e32 v32, v62, v32
	v_pk_mul_f32 v[64:65], v[52:53], v[52:53]
	v_add_f32_e32 v32, v63, v32
	v_add_f32_e32 v32, v64, v32
	v_lshlrev_b32_e32 v56, 16, v57
	v_and_b32_e32 v57, 0xffff0000, v57
	v_pk_mul_f32 v[66:67], v[54:55], v[54:55]
	v_add_f32_e32 v32, v65, v32
	v_pk_add_f32 v[56:57], v[34:35], v[56:57]
	v_add_f32_e32 v32, v66, v32
	v_pk_mul_f32 v[68:69], v[56:57], v[56:57]
	v_add_f32_e32 v32, v67, v32
	v_add_f32_e32 v32, v68, v32
	v_add_f32_e32 v32, v69, v32
	v_mov_b32_e32 v33, v32
	s_nop 1
	v_permlane16_swap_b32_e32 v32, v33
	v_cvt_pk_bf16_f32 v34, v44, v45
	v_cvt_pk_bf16_f32 v35, v46, v47
	v_cvt_pk_bf16_f32 v36, v40, v41
	v_cvt_pk_bf16_f32 v37, v42, v43
	s_waitcnt lgkmcnt(0)
	v_add_f32_e32 v32, v32, v33
	v_mov_b32_e32 v33, v32
	s_nop 1
	v_permlane32_swap_b32_e32 v32, v33
	v_cvt_pk_bf16_f32 v38, v50, v51
	v_cvt_pk_bf16_f32 v39, v52, v53
	v_cvt_pk_bf16_f32 v40, v54, v55
	v_cvt_pk_bf16_f32 v41, v56, v57
	s_nop 1
	v_permlane16_swap_b32_e32 v34, v38
	v_permlane16_swap_b32_e32 v35, v39
	v_permlane16_swap_b32_e32 v36, v40
	v_permlane16_swap_b32_e32 v37, v41
	v_permlane32_swap_b32_e32 v34, v38
	v_permlane32_swap_b32_e32 v35, v39
	v_permlane32_swap_b32_e32 v36, v40
	v_permlane32_swap_b32_e32 v37, v41
	v_lshl_add_u64 v[238:239], v[58:59], 0, v[236:237]
	global_store_dwordx4 v[238:239], v[34:37], off
	global_store_dwordx4 v[238:239], v[38:41], off offset:64
	s_and_saveexec_b64 s[4:5], s[6:7]
	s_cbranch_execz .LBB0_1567
	s_waitcnt lgkmcnt(0)
	v_add_f32_e32 v34, v32, v33
	v_lshlrev_b64 v[32:33], 6, v[48:49]
	v_lshl_add_u64 v[32:33], s[14:15], 0, v[32:33]
	v_lshl_add_u64 v[32:33], s[26:27], 2, v[32:33]
	s_lshl_b32 s8, s40, 2
	v_lshl_add_u64 v[32:33], v[32:33], 0, s[8:9]
	global_store_dword v[32:33], v34, off
.LBB0_1567:
	s_or_b64 exec, exec, s[4:5]
	v_add_u32_e32 v32, 0xa0, v140
	s_waitcnt lgkmcnt(0)
	v_ashrrev_i32_e32 v33, 31, v32
	v_lshlrev_b64 v[34:35], 11, v[32:33]
	v_lshl_add_u64 v[34:35], s[12:13], 0, v[34:35]
	v_lshl_add_u64 v[42:43], v[138:139], 1, v[34:35]
	v_lshl_add_u64 v[234:235], v[42:43], 0, v[236:237]
	global_load_dwordx4 v[34:37], v[234:235], off
	global_load_dwordx4 v[38:41], v[234:235], off offset:64
	s_waitcnt vmcnt(0)
	v_permlane32_swap_b32_e32 v34, v38
	v_permlane32_swap_b32_e32 v35, v39
	v_permlane32_swap_b32_e32 v36, v40
	v_permlane32_swap_b32_e32 v37, v41
	v_permlane16_swap_b32_e32 v34, v38
	v_permlane16_swap_b32_e32 v35, v39
	v_permlane16_swap_b32_e32 v36, v40
	v_permlane16_swap_b32_e32 v37, v41
	v_lshlrev_b32_e32 v44, 16, v34
	v_and_b32_e32 v45, 0xffff0000, v34
	v_lshlrev_b32_e32 v34, 16, v35
	v_and_b32_e32 v35, 0xffff0000, v35
	v_lshlrev_b32_e32 v46, 16, v36
	v_and_b32_e32 v47, 0xffff0000, v36
	v_lshlrev_b32_e32 v36, 16, v37
	v_and_b32_e32 v37, 0xffff0000, v37
	s_waitcnt vmcnt(0)
	v_lshlrev_b32_e32 v48, 16, v38
	v_and_b32_e32 v49, 0xffff0000, v38
	v_lshlrev_b32_e32 v38, 16, v39
	v_and_b32_e32 v39, 0xffff0000, v39
	v_lshlrev_b32_e32 v50, 16, v40
	v_and_b32_e32 v51, 0xffff0000, v40
	v_pk_add_f32 v[28:29], v[28:29], v[44:45]
	v_pk_add_f32 v[30:31], v[30:31], v[34:35]
	v_pk_add_f32 v[26:27], v[26:27], v[36:37]
	v_pk_add_f32 v[36:37], v[22:23], v[38:39]
	v_pk_add_f32 v[38:39], v[16:17], v[50:51]
	v_pk_mul_f32 v[16:17], v[28:29], v[28:29]
	v_pk_add_f32 v[34:35], v[20:21], v[48:49]
	v_pk_mul_f32 v[20:21], v[30:31], v[30:31]
	v_add_f32_e32 v16, v16, v17
	v_pk_add_f32 v[24:25], v[24:25], v[46:47]
	v_add_f32_e32 v16, v20, v16
	v_pk_mul_f32 v[22:23], v[24:25], v[24:25]
	v_add_f32_e32 v16, v21, v16
	v_add_f32_e32 v16, v22, v16
	v_pk_mul_f32 v[44:45], v[26:27], v[26:27]
	v_add_f32_e32 v16, v23, v16
	v_add_f32_e32 v16, v44, v16
	v_pk_mul_f32 v[46:47], v[34:35], v[34:35]
	v_add_f32_e32 v16, v45, v16
	v_add_f32_e32 v16, v46, v16
	v_pk_mul_f32 v[48:49], v[36:37], v[36:37]
	v_add_f32_e32 v16, v47, v16
	v_add_f32_e32 v16, v48, v16
	v_lshlrev_b32_e32 v40, 16, v41
	v_and_b32_e32 v41, 0xffff0000, v41
	v_pk_mul_f32 v[50:51], v[38:39], v[38:39]
	v_add_f32_e32 v16, v49, v16
	v_pk_add_f32 v[40:41], v[18:19], v[40:41]
	v_add_f32_e32 v16, v50, v16
	v_pk_mul_f32 v[52:53], v[40:41], v[40:41]
	v_add_f32_e32 v16, v51, v16
	v_add_f32_e32 v16, v52, v16
	v_add_f32_e32 v16, v53, v16
	v_mov_b32_e32 v17, v16
	s_nop 1
	v_permlane16_swap_b32_e32 v16, v17
	v_cvt_pk_bf16_f32 v18, v28, v29
	v_cvt_pk_bf16_f32 v19, v30, v31
	v_cvt_pk_bf16_f32 v20, v24, v25
	v_cvt_pk_bf16_f32 v21, v26, v27
	s_waitcnt lgkmcnt(0)
	v_add_f32_e32 v16, v16, v17
	v_mov_b32_e32 v17, v16
	s_nop 1
	v_permlane32_swap_b32_e32 v16, v17
	v_cvt_pk_bf16_f32 v22, v34, v35
	v_cvt_pk_bf16_f32 v23, v36, v37
	v_cvt_pk_bf16_f32 v24, v38, v39
	v_cvt_pk_bf16_f32 v25, v40, v41
	s_nop 1
	v_permlane16_swap_b32_e32 v18, v22
	v_permlane16_swap_b32_e32 v19, v23
	v_permlane16_swap_b32_e32 v20, v24
	v_permlane16_swap_b32_e32 v21, v25
	v_permlane32_swap_b32_e32 v18, v22
	v_permlane32_swap_b32_e32 v19, v23
	v_permlane32_swap_b32_e32 v20, v24
	v_permlane32_swap_b32_e32 v21, v25
	v_lshl_add_u64 v[238:239], v[42:43], 0, v[236:237]
	global_store_dwordx4 v[238:239], v[18:21], off
	global_store_dwordx4 v[238:239], v[22:25], off offset:64
	s_and_saveexec_b64 s[4:5], s[6:7]
	s_cbranch_execz .LBB0_1569
	s_waitcnt lgkmcnt(0)
	v_add_f32_e32 v18, v16, v17
	v_lshlrev_b64 v[16:17], 6, v[32:33]
	v_lshl_add_u64 v[16:17], s[14:15], 0, v[16:17]
	v_lshl_add_u64 v[16:17], s[26:27], 2, v[16:17]
	s_lshl_b32 s8, s40, 2
	v_lshl_add_u64 v[16:17], v[16:17], 0, s[8:9]
	global_store_dword v[16:17], v18, off
.LBB0_1569:
	s_or_b64 exec, exec, s[4:5]
	v_add_u32_e32 v16, 0xb0, v140
	s_waitcnt lgkmcnt(0)
	v_ashrrev_i32_e32 v17, 31, v16
	v_lshlrev_b64 v[18:19], 11, v[16:17]
	v_lshl_add_u64 v[18:19], s[12:13], 0, v[18:19]
	v_lshl_add_u64 v[26:27], v[138:139], 1, v[18:19]
	v_lshl_add_u64 v[234:235], v[26:27], 0, v[236:237]
	global_load_dwordx4 v[18:21], v[234:235], off
	global_load_dwordx4 v[22:25], v[234:235], off offset:64
	s_waitcnt vmcnt(0)
	v_permlane32_swap_b32_e32 v18, v22
	v_permlane32_swap_b32_e32 v19, v23
	v_permlane32_swap_b32_e32 v20, v24
	v_permlane32_swap_b32_e32 v21, v25
	v_permlane16_swap_b32_e32 v18, v22
	v_permlane16_swap_b32_e32 v19, v23
	v_permlane16_swap_b32_e32 v20, v24
	v_permlane16_swap_b32_e32 v21, v25
	v_lshlrev_b32_e32 v28, 16, v18
	v_and_b32_e32 v29, 0xffff0000, v18
	v_lshlrev_b32_e32 v18, 16, v19
	v_and_b32_e32 v19, 0xffff0000, v19
	v_lshlrev_b32_e32 v30, 16, v20
	v_and_b32_e32 v31, 0xffff0000, v20
	v_lshlrev_b32_e32 v20, 16, v21
	v_and_b32_e32 v21, 0xffff0000, v21
	s_waitcnt vmcnt(0)
	v_lshlrev_b32_e32 v32, 16, v22
	v_and_b32_e32 v33, 0xffff0000, v22
	v_lshlrev_b32_e32 v22, 16, v23
	v_and_b32_e32 v23, 0xffff0000, v23
	v_lshlrev_b32_e32 v34, 16, v24
	v_and_b32_e32 v35, 0xffff0000, v24
	v_pk_add_f32 v[12:13], v[12:13], v[28:29]
	v_pk_add_f32 v[14:15], v[14:15], v[18:19]
	v_pk_add_f32 v[10:11], v[10:11], v[20:21]
	v_pk_add_f32 v[20:21], v[6:7], v[22:23]
	v_pk_add_f32 v[22:23], v[0:1], v[34:35]
	v_pk_mul_f32 v[0:1], v[12:13], v[12:13]
	v_pk_add_f32 v[18:19], v[4:5], v[32:33]
	v_pk_mul_f32 v[4:5], v[14:15], v[14:15]
	v_add_f32_e32 v0, v0, v1
	v_pk_add_f32 v[8:9], v[8:9], v[30:31]
	v_add_f32_e32 v0, v4, v0
	v_pk_mul_f32 v[6:7], v[8:9], v[8:9]
	v_add_f32_e32 v0, v5, v0
	v_add_f32_e32 v0, v6, v0
	v_pk_mul_f32 v[28:29], v[10:11], v[10:11]
	v_add_f32_e32 v0, v7, v0
	v_add_f32_e32 v0, v28, v0
	v_pk_mul_f32 v[30:31], v[18:19], v[18:19]
	v_add_f32_e32 v0, v29, v0
	v_add_f32_e32 v0, v30, v0
	v_pk_mul_f32 v[32:33], v[20:21], v[20:21]
	v_add_f32_e32 v0, v31, v0
	v_add_f32_e32 v0, v32, v0
	v_lshlrev_b32_e32 v24, 16, v25
	v_and_b32_e32 v25, 0xffff0000, v25
	v_pk_mul_f32 v[34:35], v[22:23], v[22:23]
	v_add_f32_e32 v0, v33, v0
	v_pk_add_f32 v[24:25], v[2:3], v[24:25]
	v_add_f32_e32 v0, v34, v0
	v_pk_mul_f32 v[36:37], v[24:25], v[24:25]
	v_add_f32_e32 v0, v35, v0
	v_add_f32_e32 v0, v36, v0
	v_add_f32_e32 v0, v37, v0
	v_mov_b32_e32 v1, v0
	s_nop 1
	v_permlane16_swap_b32_e32 v0, v1
	v_cvt_pk_bf16_f32 v2, v12, v13
	v_cvt_pk_bf16_f32 v3, v14, v15
	v_cvt_pk_bf16_f32 v4, v8, v9
	v_cvt_pk_bf16_f32 v5, v10, v11
	s_waitcnt lgkmcnt(0)
	v_add_f32_e32 v0, v0, v1
	v_mov_b32_e32 v1, v0
	s_nop 1
	v_permlane32_swap_b32_e32 v0, v1
	v_cvt_pk_bf16_f32 v6, v18, v19
	v_cvt_pk_bf16_f32 v7, v20, v21
	v_cvt_pk_bf16_f32 v8, v22, v23
	v_cvt_pk_bf16_f32 v9, v24, v25
	s_nop 1
	v_permlane16_swap_b32_e32 v2, v6
	v_permlane16_swap_b32_e32 v3, v7
	v_permlane16_swap_b32_e32 v4, v8
	v_permlane16_swap_b32_e32 v5, v9
	v_permlane32_swap_b32_e32 v2, v6
	v_permlane32_swap_b32_e32 v3, v7
	v_permlane32_swap_b32_e32 v4, v8
	v_permlane32_swap_b32_e32 v5, v9
	v_lshl_add_u64 v[238:239], v[26:27], 0, v[236:237]
	global_store_dwordx4 v[238:239], v[2:5], off
	global_store_dwordx4 v[238:239], v[6:9], off offset:64
	s_and_saveexec_b64 s[4:5], s[6:7]
	s_cbranch_execz .LBB0_1571
	s_waitcnt lgkmcnt(0)
	v_add_f32_e32 v2, v0, v1
	v_lshlrev_b64 v[0:1], 6, v[16:17]
	v_lshl_add_u64 v[0:1], s[14:15], 0, v[0:1]
	v_lshl_add_u64 v[0:1], s[26:27], 2, v[0:1]
	s_lshl_b32 s8, s40, 2
	v_lshl_add_u64 v[0:1], v[0:1], 0, s[8:9]
	global_store_dword v[0:1], v2, off
